# GEMM K-loops: s_setprio 0/1 pair between the two 16-MFMA halves removed, redundant lgkmcnt(0) after the opening barrier removed
# speedup vs baseline: 1.0620x; 1.0007x over previous
; #define PG8_STAGE(bufoff, gbase, voff) do { _Pragma("unroll") for (int _i = 0; _i < 2; ++_i) \
;         __builtin_amdgcn_global_load_lds((const unsigned*)((const char*)(gbase) + (voff)[_i]), (PG8_LAS unsigned*)(lds + (bufoff) + ldsw + _i * 8192), 16, 0, 0); } while (0)
; #define PG8_LDA(dst, b, h) do { _Pragma("unroll") for (int m = 0; m < 4; ++m) _Pragma("unroll") for (int k = 0; k < 2; ++k) dst[m][k] = *(const PG8_LAS bf16x8*)(lds + PG8_SA(b, h) + aoff + m * 2048 + k * 1024); } while (0)
; #define PG8_LDB(dst, b, h) do { _Pragma("unroll") for (int n = 0; n < 2; ++n) _Pragma("unroll") for (int k = 0; k < 2; ++k) dst[n][k] = *(const PG8_LAS bf16x8*)(lds + PG8_SB(b, h) + boff + n * 2048 + k * 1024); } while (0)
; #define PG8_MMA(ai, bj, At, Bt) do { __builtin_amdgcn_s_setprio(1); _Pragma("unroll") for (int m = 0; m < 4; ++m) _Pragma("unroll") for (int n = 0; n < 2; ++n) _Pragma("unroll") for (int k = 0; k < 2; ++k) \
;         acc[ai][bj][m][n] = __builtin_amdgcn_mfma_f32_16x16x32_bf16(Bt[n][k], At[m][k], acc[ai][bj][m][n], 0, 0, 0); __builtin_amdgcn_s_setprio(0); } while (0)
; #define PG8_WAIT_V(n) asm volatile("s_waitcnt vmcnt(" #n ")" ::: "memory")
; #define PG8_WAIT_L(n) asm volatile("s_waitcnt lgkmcnt(" #n ")" ::: "memory")
; #define PG8_BAR __builtin_amdgcn_s_barrier()
; #define PG8_SCHED __builtin_amdgcn_sched_barrier(0)
; template <class Epi, class Sched, bool ALIGN_EPI = false, bool SP2 = false>
; __device__ __forceinline__ void gemm_phase(PG8_LAS unsigned char* lds, int tid_in, const Gemm g, const Sched& S, const Epi& E) {
;     ...
;             if constexpr (SP2) {
;             PG8_LDB(B0, 0, 0); PG8_LDB(B1, 0, 1); PG8_SCHED; PG8_LDA(At, 0, 0); PG8_STAGE(PG8_SA(1, 1), a1 + hstepA, voffA);
;             PG8_WAIT_V(8); PG8_WAIT_L(0); PG8_BAR; PG8_MMA(0, 0, At, B0); PG8_MMA(0, 1, At, B1); PG8_BAR; PG8_SCHED;
;             PG8_LDA(At, 0, 1); PG8_STAGE(PG8_SB(0, 0), b2, voffB); PG8_STAGE(PG8_SB(0, 1), b2 + hstepB, voffB); PG8_STAGE(PG8_SA(0, 0), a2, voffA);
;             PG8_WAIT_V(8); PG8_WAIT_L(0); PG8_BAR; PG8_MMA(1, 0, At, B0); PG8_MMA(1, 1, At, B1); PG8_BAR; PG8_SCHED;
.LBB0_282:
	s_add_i32 s26, s18, 2
	s_add_u32 s30, s14, 0x80
	s_addc_u32 s19, s15, 0
	s_add_i32 s44, 0, 0x10000
	s_cmp_eq_u32 s7, s18
	s_cselect_b32 s19, s63, s19
	s_cselect_b32 s18, s62, s30
	v_add_u32_e32 v0, s44, v157
	s_cselect_b32 s31, s29, s21
	s_cselect_b32 s30, s28, s20
	s_add_i32 s45, 0, 0x14000
	s_waitcnt lgkmcnt(0)
	ds_read_b128 v[130:133], v0
	ds_read_b128 v[134:137], v0 offset:1024
	ds_read_b128 v[138:141], v0 offset:2048
	ds_read_b128 v[142:145], v0 offset:3072
	v_add_u32_e32 v0, s45, v157
	ds_read_b128 v[162:165], v0
	ds_read_b128 v[166:169], v0 offset:1024
	ds_read_b128 v[170:173], v0 offset:2048
	ds_read_b128 v[174:177], v0 offset:3072
	v_lshl_add_u64 v[194:195], s[14:15], 0, v[158:159]
	s_add_i32 m0, s97, 0xc000
	ds_read_b128 v[178:181], v212
	ds_read_b128 v[182:185], v212 offset:1024
	ds_read_b128 v[186:189], v212 offset:2048
	ds_read_b128 v[190:193], v212 offset:3072
	ds_read_b128 v[230:233], v212 offset:4096
	ds_read_b128 v[234:237], v212 offset:5120
	ds_read_b128 v[238:241], v212 offset:6144
	ds_read_b128 v[242:245], v212 offset:7168
	global_load_lds_dwordx4 v[194:195], off
	v_lshl_add_u64 v[194:195], s[14:15], 0, v[160:161]
	s_add_i32 m0, s97, 0xe000
	s_nop 0
	global_load_lds_dwordx4 v[194:195], off
	s_waitcnt vmcnt(8)
	s_waitcnt lgkmcnt(0)
	s_barrier
	s_setprio 1
	v_mfma_f32_16x16x32_bf16 v[126:129], v[130:133], v[178:181], v[126:129]
	v_mfma_f32_16x16x32_bf16 v[122:125], v[138:141], v[178:181], v[122:125]
	v_mfma_f32_16x16x32_bf16 v[110:113], v[130:133], v[186:189], v[110:113]
	v_mfma_f32_16x16x32_bf16 v[106:109], v[138:141], v[186:189], v[106:109]
	v_mfma_f32_16x16x32_bf16 v[94:97], v[130:133], v[230:233], v[94:97]
	v_mfma_f32_16x16x32_bf16 v[90:93], v[138:141], v[230:233], v[90:93]
	v_mfma_f32_16x16x32_bf16 v[78:81], v[130:133], v[238:241], v[78:81]
	v_mfma_f32_16x16x32_bf16 v[74:77], v[138:141], v[238:241], v[74:77]
	v_mfma_f32_16x16x32_bf16 v[126:129], v[134:137], v[182:185], v[126:129]
	v_mfma_f32_16x16x32_bf16 v[122:125], v[142:145], v[182:185], v[122:125]
	v_mfma_f32_16x16x32_bf16 v[110:113], v[134:137], v[190:193], v[110:113]
	v_mfma_f32_16x16x32_bf16 v[106:109], v[142:145], v[190:193], v[106:109]
	v_mfma_f32_16x16x32_bf16 v[94:97], v[134:137], v[234:237], v[94:97]
	v_mfma_f32_16x16x32_bf16 v[90:93], v[142:145], v[234:237], v[90:93]
	v_mfma_f32_16x16x32_bf16 v[78:81], v[134:137], v[242:245], v[78:81]
	v_mfma_f32_16x16x32_bf16 v[74:77], v[142:145], v[242:245], v[74:77]
	v_mfma_f32_16x16x32_bf16 v[118:121], v[162:165], v[178:181], v[118:121]
	v_mfma_f32_16x16x32_bf16 v[114:117], v[170:173], v[178:181], v[114:117]
	v_mfma_f32_16x16x32_bf16 v[102:105], v[162:165], v[186:189], v[102:105]
	v_mfma_f32_16x16x32_bf16 v[98:101], v[170:173], v[186:189], v[98:101]
	v_mfma_f32_16x16x32_bf16 v[86:89], v[162:165], v[230:233], v[86:89]
	v_mfma_f32_16x16x32_bf16 v[82:85], v[170:173], v[230:233], v[82:85]
	v_mfma_f32_16x16x32_bf16 v[70:73], v[162:165], v[238:241], v[70:73]
	v_mfma_f32_16x16x32_bf16 v[66:69], v[170:173], v[238:241], v[66:69]
	v_mfma_f32_16x16x32_bf16 v[118:121], v[166:169], v[182:185], v[118:121]
	v_mfma_f32_16x16x32_bf16 v[114:117], v[174:177], v[182:185], v[114:117]
	v_mfma_f32_16x16x32_bf16 v[102:105], v[166:169], v[190:193], v[102:105]
	v_mfma_f32_16x16x32_bf16 v[98:101], v[174:177], v[190:193], v[98:101]
	v_mfma_f32_16x16x32_bf16 v[86:89], v[166:169], v[234:237], v[86:89]
	v_mfma_f32_16x16x32_bf16 v[82:85], v[174:177], v[234:237], v[82:85]
	v_mfma_f32_16x16x32_bf16 v[70:73], v[166:169], v[242:245], v[70:73]
	v_mfma_f32_16x16x32_bf16 v[66:69], v[174:177], v[242:245], v[66:69]
	s_setprio 0
	s_barrier
	s_add_i32 s44, s44, s96
	v_lshl_add_u64 v[194:195], s[30:31], 0, v[148:149]
	s_mov_b32 m0, s44
	ds_read_b128 v[178:181], v212 offset:16384
	ds_read_b128 v[182:185], v212 offset:17408
	ds_read_b128 v[186:189], v212 offset:18432
	ds_read_b128 v[190:193], v212 offset:19456
	ds_read_b128 v[230:233], v212 offset:20480
	ds_read_b128 v[234:237], v212 offset:21504
	ds_read_b128 v[238:241], v212 offset:22528
	ds_read_b128 v[242:245], v212 offset:23552
	global_load_lds_dwordx4 v[194:195], off
	s_add_i32 m0, s44, 0x2000
	v_lshl_add_u64 v[246:247], s[30:31], 0, v[152:153]
	s_add_u32 s30, s30, s33
	s_addc_u32 s31, s31, 0
	s_add_i32 s44, s45, s96
	global_load_lds_dwordx4 v[246:247], off
	v_lshl_add_u64 v[248:249], s[30:31], 0, v[148:149]
	s_mov_b32 m0, s44
	v_lshl_add_u64 v[250:251], s[30:31], 0, v[152:153]
	global_load_lds_dwordx4 v[248:249], off
	s_add_i32 m0, s44, 0x2000
	v_lshl_add_u64 v[222:223], s[18:19], 0, v[146:147]
	global_load_lds_dwordx4 v[250:251], off
	s_mov_b32 m0, s97
	v_lshl_add_u64 v[224:225], s[18:19], 0, v[150:151]
	global_load_lds_dwordx4 v[222:223], off
	s_mov_b32 m0, s4
	s_nop 0
	global_load_lds_dwordx4 v[224:225], off
	s_waitcnt vmcnt(8)
	s_waitcnt lgkmcnt(0)
	s_barrier
; #define PG8_STAGE(bufoff, gbase, voff) do { _Pragma("unroll") for (int _i = 0; _i < 2; ++_i) \
;         __builtin_amdgcn_global_load_lds((const unsigned*)((const char*)(gbase) + (voff)[_i]), (PG8_LAS unsigned*)(lds + (bufoff) + ldsw + _i * 8192), 16, 0, 0); } while (0)
; #define PG8_LDA(dst, b, h) do { _Pragma("unroll") for (int m = 0; m < 4; ++m) _Pragma("unroll") for (int k = 0; k < 2; ++k) dst[m][k] = *(const PG8_LAS bf16x8*)(lds + PG8_SA(b, h) + aoff + m * 2048 + k * 1024); } while (0)
; #define PG8_LDB(dst, b, h) do { _Pragma("unroll") for (int n = 0; n < 2; ++n) _Pragma("unroll") for (int k = 0; k < 2; ++k) dst[n][k] = *(const PG8_LAS bf16x8*)(lds + PG8_SB(b, h) + boff + n * 2048 + k * 1024); } while (0)
; #define PG8_MMA(ai, bj, At, Bt) do { __builtin_amdgcn_s_setprio(1); _Pragma("unroll") for (int m = 0; m < 4; ++m) _Pragma("unroll") for (int n = 0; n < 2; ++n) _Pragma("unroll") for (int k = 0; k < 2; ++k) \
;         acc[ai][bj][m][n] = __builtin_amdgcn_mfma_f32_16x16x32_bf16(Bt[n][k], At[m][k], acc[ai][bj][m][n], 0, 0, 0); __builtin_amdgcn_s_setprio(0); } while (0)
; #define PG8_WAIT_V(n) asm volatile("s_waitcnt vmcnt(" #n ")" ::: "memory")
; #define PG8_WAIT_L(n) asm volatile("s_waitcnt lgkmcnt(" #n ")" ::: "memory")
; #define PG8_BAR __builtin_amdgcn_s_barrier()
; #define PG8_SCHED __builtin_amdgcn_sched_barrier(0)
; template <class Epi, class Sched, bool ALIGN_EPI = false, bool SP2 = false>
; __device__ __forceinline__ void gemm_phase(PG8_LAS unsigned char* lds, int tid_in, const Gemm g, const Sched& S, const Epi& E) {
;     ...
;             PG8_WAIT_V(8); PG8_WAIT_L(0); PG8_BAR; PG8_MMA(1, 0, At, B0); PG8_MMA(1, 1, At, B1); PG8_BAR; PG8_SCHED;
;             PG8_LDB(B0, 1, 0); PG8_LDB(B1, 1, 1); PG8_SCHED; PG8_LDA(At, 1, 0); PG8_STAGE(PG8_SA(0, 1), a2 + hstepA, voffA);
;             PG8_WAIT_V(8); PG8_WAIT_L(0); PG8_BAR; PG8_MMA(0, 0, At, B0); PG8_MMA(0, 1, At, B1); PG8_BAR; PG8_SCHED;
	s_setprio 1
	v_mfma_f32_16x16x32_bf16 v[62:65], v[130:133], v[178:181], v[62:65]
	v_mfma_f32_16x16x32_bf16 v[58:61], v[138:141], v[178:181], v[58:61]
	v_mfma_f32_16x16x32_bf16 v[46:49], v[130:133], v[186:189], v[46:49]
	v_mfma_f32_16x16x32_bf16 v[42:45], v[138:141], v[186:189], v[42:45]
	v_mfma_f32_16x16x32_bf16 v[30:33], v[130:133], v[230:233], v[30:33]
	v_mfma_f32_16x16x32_bf16 v[26:29], v[138:141], v[230:233], v[26:29]
	v_mfma_f32_16x16x32_bf16 v[14:17], v[130:133], v[238:241], v[14:17]
	v_mfma_f32_16x16x32_bf16 v[10:13], v[138:141], v[238:241], v[10:13]
	v_mfma_f32_16x16x32_bf16 v[62:65], v[134:137], v[182:185], v[62:65]
	v_mfma_f32_16x16x32_bf16 v[58:61], v[142:145], v[182:185], v[58:61]
	v_mfma_f32_16x16x32_bf16 v[46:49], v[134:137], v[190:193], v[46:49]
	v_mfma_f32_16x16x32_bf16 v[42:45], v[142:145], v[190:193], v[42:45]
	v_mfma_f32_16x16x32_bf16 v[30:33], v[134:137], v[234:237], v[30:33]
	v_mfma_f32_16x16x32_bf16 v[26:29], v[142:145], v[234:237], v[26:29]
	v_mfma_f32_16x16x32_bf16 v[14:17], v[134:137], v[242:245], v[14:17]
	v_mfma_f32_16x16x32_bf16 v[10:13], v[142:145], v[242:245], v[10:13]
	v_mfma_f32_16x16x32_bf16 v[54:57], v[162:165], v[178:181], v[54:57]
	v_mfma_f32_16x16x32_bf16 v[50:53], v[170:173], v[178:181], v[50:53]
	v_mfma_f32_16x16x32_bf16 v[38:41], v[162:165], v[186:189], v[38:41]
	v_mfma_f32_16x16x32_bf16 v[34:37], v[170:173], v[186:189], v[34:37]
	v_mfma_f32_16x16x32_bf16 v[22:25], v[162:165], v[230:233], v[22:25]
	v_mfma_f32_16x16x32_bf16 v[18:21], v[170:173], v[230:233], v[18:21]
	v_mfma_f32_16x16x32_bf16 v[6:9], v[162:165], v[238:241], v[6:9]
	v_mfma_f32_16x16x32_bf16 v[2:5], v[170:173], v[238:241], v[2:5]
	v_mfma_f32_16x16x32_bf16 v[54:57], v[166:169], v[182:185], v[54:57]
	v_mfma_f32_16x16x32_bf16 v[50:53], v[174:177], v[182:185], v[50:53]
	v_mfma_f32_16x16x32_bf16 v[38:41], v[166:169], v[190:193], v[38:41]
	v_mfma_f32_16x16x32_bf16 v[34:37], v[174:177], v[190:193], v[34:37]
	v_mfma_f32_16x16x32_bf16 v[22:25], v[166:169], v[234:237], v[22:25]
	v_mfma_f32_16x16x32_bf16 v[18:21], v[174:177], v[234:237], v[18:21]
	v_mfma_f32_16x16x32_bf16 v[6:9], v[166:169], v[242:245], v[6:9]
	v_mfma_f32_16x16x32_bf16 v[2:5], v[174:177], v[242:245], v[2:5]
	s_setprio 0
	s_barrier
	s_add_i32 s30, 0, 0x18000
	v_add_u32_e32 v0, s30, v157
	s_add_i32 s31, 0, 0x1c000
	ds_read_b128 v[130:133], v0
	ds_read_b128 v[134:137], v0 offset:1024
	ds_read_b128 v[138:141], v0 offset:2048
	ds_read_b128 v[142:145], v0 offset:3072
	v_add_u32_e32 v0, s31, v157
	ds_read_b128 v[162:165], v0
	ds_read_b128 v[166:169], v0 offset:1024
	ds_read_b128 v[170:173], v0 offset:2048
	ds_read_b128 v[174:177], v0 offset:3072
	s_add_u32 s18, s18, s38
	s_addc_u32 s19, s19, 0
	s_mov_b32 m0, s5
	v_lshl_add_u64 v[226:227], s[18:19], 0, v[146:147]
	ds_read_b128 v[178:181], v212 offset:32768
	ds_read_b128 v[182:185], v212 offset:33792
	ds_read_b128 v[186:189], v212 offset:34816
	ds_read_b128 v[190:193], v212 offset:35840
	ds_read_b128 v[230:233], v212 offset:36864
	ds_read_b128 v[234:237], v212 offset:37888
	ds_read_b128 v[238:241], v212 offset:38912
	ds_read_b128 v[242:245], v212 offset:39936
	global_load_lds_dwordx4 v[226:227], off
	v_lshl_add_u64 v[226:227], s[18:19], 0, v[150:151]
	s_mov_b32 m0, s6
	s_nop 0
	global_load_lds_dwordx4 v[226:227], off
	s_waitcnt vmcnt(8)
	s_waitcnt lgkmcnt(0)
	s_barrier
	s_setprio 1
	v_mfma_f32_16x16x32_bf16 v[126:129], v[130:133], v[178:181], v[126:129]
	v_mfma_f32_16x16x32_bf16 v[122:125], v[138:141], v[178:181], v[122:125]
	v_mfma_f32_16x16x32_bf16 v[110:113], v[130:133], v[186:189], v[110:113]
	v_mfma_f32_16x16x32_bf16 v[106:109], v[138:141], v[186:189], v[106:109]
	v_mfma_f32_16x16x32_bf16 v[94:97], v[130:133], v[230:233], v[94:97]
	v_mfma_f32_16x16x32_bf16 v[90:93], v[138:141], v[230:233], v[90:93]
	v_mfma_f32_16x16x32_bf16 v[78:81], v[130:133], v[238:241], v[78:81]
	v_mfma_f32_16x16x32_bf16 v[74:77], v[138:141], v[238:241], v[74:77]
	v_mfma_f32_16x16x32_bf16 v[126:129], v[134:137], v[182:185], v[126:129]
	v_mfma_f32_16x16x32_bf16 v[122:125], v[142:145], v[182:185], v[122:125]
	v_mfma_f32_16x16x32_bf16 v[110:113], v[134:137], v[190:193], v[110:113]
	v_mfma_f32_16x16x32_bf16 v[106:109], v[142:145], v[190:193], v[106:109]
	v_mfma_f32_16x16x32_bf16 v[94:97], v[134:137], v[234:237], v[94:97]
	v_mfma_f32_16x16x32_bf16 v[90:93], v[142:145], v[234:237], v[90:93]
	v_mfma_f32_16x16x32_bf16 v[78:81], v[134:137], v[242:245], v[78:81]
	v_mfma_f32_16x16x32_bf16 v[74:77], v[142:145], v[242:245], v[74:77]
	v_mfma_f32_16x16x32_bf16 v[118:121], v[162:165], v[178:181], v[118:121]
	v_mfma_f32_16x16x32_bf16 v[114:117], v[170:173], v[178:181], v[114:117]
	v_mfma_f32_16x16x32_bf16 v[102:105], v[162:165], v[186:189], v[102:105]
	v_mfma_f32_16x16x32_bf16 v[98:101], v[170:173], v[186:189], v[98:101]
	v_mfma_f32_16x16x32_bf16 v[86:89], v[162:165], v[230:233], v[86:89]
	v_mfma_f32_16x16x32_bf16 v[82:85], v[170:173], v[230:233], v[82:85]
	v_mfma_f32_16x16x32_bf16 v[70:73], v[162:165], v[238:241], v[70:73]
	v_mfma_f32_16x16x32_bf16 v[66:69], v[170:173], v[238:241], v[66:69]
	v_mfma_f32_16x16x32_bf16 v[118:121], v[166:169], v[182:185], v[118:121]
	v_mfma_f32_16x16x32_bf16 v[114:117], v[174:177], v[182:185], v[114:117]
	v_mfma_f32_16x16x32_bf16 v[102:105], v[166:169], v[190:193], v[102:105]
	v_mfma_f32_16x16x32_bf16 v[98:101], v[174:177], v[190:193], v[98:101]
	v_mfma_f32_16x16x32_bf16 v[86:89], v[166:169], v[234:237], v[86:89]
	v_mfma_f32_16x16x32_bf16 v[82:85], v[174:177], v[234:237], v[82:85]
	v_mfma_f32_16x16x32_bf16 v[70:73], v[166:169], v[242:245], v[70:73]
	v_mfma_f32_16x16x32_bf16 v[66:69], v[174:177], v[242:245], v[66:69]
	s_setprio 0
	s_barrier
; #define PG8_STAGE(bufoff, gbase, voff) do { _Pragma("unroll") for (int _i = 0; _i < 2; ++_i) \
;         __builtin_amdgcn_global_load_lds((const unsigned*)((const char*)(gbase) + (voff)[_i]), (PG8_LAS unsigned*)(lds + (bufoff) + ldsw + _i * 8192), 16, 0, 0); } while (0)
; #define PG8_LDA(dst, b, h) do { _Pragma("unroll") for (int m = 0; m < 4; ++m) _Pragma("unroll") for (int k = 0; k < 2; ++k) dst[m][k] = *(const PG8_LAS bf16x8*)(lds + PG8_SA(b, h) + aoff + m * 2048 + k * 1024); } while (0)
; #define PG8_MMA(ai, bj, At, Bt) do { __builtin_amdgcn_s_setprio(1); _Pragma("unroll") for (int m = 0; m < 4; ++m) _Pragma("unroll") for (int n = 0; n < 2; ++n) _Pragma("unroll") for (int k = 0; k < 2; ++k) \
;         acc[ai][bj][m][n] = __builtin_amdgcn_mfma_f32_16x16x32_bf16(Bt[n][k], At[m][k], acc[ai][bj][m][n], 0, 0, 0); __builtin_amdgcn_s_setprio(0); } while (0)
; #define PG8_WAIT_V(n) asm volatile("s_waitcnt vmcnt(" #n ")" ::: "memory")
; #define PG8_WAIT_L(n) asm volatile("s_waitcnt lgkmcnt(" #n ")" ::: "memory")
; #define PG8_BAR __builtin_amdgcn_s_barrier()
; #define PG8_SCHED __builtin_amdgcn_sched_barrier(0)
; template <class Epi, class Sched, bool ALIGN_EPI = false, bool SP2 = false>
; __device__ __forceinline__ void gemm_phase(PG8_LAS unsigned char* lds, int tid_in, const Gemm g, const Sched& S, const Epi& E) {
;     ...
;             PG8_LDA(At, 1, 1); PG8_STAGE(PG8_SB(1, 0), b3, voffB); PG8_STAGE(PG8_SB(1, 1), b3 + hstepB, voffB); PG8_STAGE(PG8_SA(1, 0), a3, voffA);
;             PG8_WAIT_V(8); PG8_WAIT_L(0); PG8_BAR; PG8_MMA(1, 0, At, B0); PG8_MMA(1, 1, At, B1); PG8_BAR; PG8_SCHED;
	s_add_i32 s18, s30, s96
	v_lshl_add_u64 v[194:195], v[194:195], 0, s[2:3]
	s_mov_b32 m0, s18
	ds_read_b128 v[178:181], v212 offset:49152
	ds_read_b128 v[182:185], v212 offset:50176
	ds_read_b128 v[186:189], v212 offset:51200
	ds_read_b128 v[190:193], v212 offset:52224
	ds_read_b128 v[230:233], v212 offset:53248
	ds_read_b128 v[234:237], v212 offset:54272
	ds_read_b128 v[238:241], v212 offset:55296
	ds_read_b128 v[242:245], v212 offset:56320
	global_load_lds_dwordx4 v[194:195], off
	v_lshl_add_u64 v[194:195], v[246:247], 0, s[2:3]
	s_add_i32 m0, s18, 0x2000
	s_add_i32 s18, s31, s96
	global_load_lds_dwordx4 v[194:195], off
	v_lshl_add_u64 v[194:195], v[248:249], 0, s[2:3]
	s_mov_b32 m0, s18
	s_nop 0
	global_load_lds_dwordx4 v[194:195], off
	v_lshl_add_u64 v[194:195], v[250:251], 0, s[2:3]
	s_add_i32 m0, s18, 0x2000
	s_nop 0
	global_load_lds_dwordx4 v[194:195], off
	v_lshl_add_u64 v[194:195], v[222:223], 0, s[2:3]
	s_mov_b32 m0, s88
	s_nop 0
	global_load_lds_dwordx4 v[194:195], off
	v_lshl_add_u64 v[194:195], v[224:225], 0, s[2:3]
	s_mov_b32 m0, s89
	s_nop 0
	global_load_lds_dwordx4 v[194:195], off
	s_waitcnt vmcnt(8)
	s_waitcnt lgkmcnt(0)
	s_barrier
	s_setprio 1
	v_mfma_f32_16x16x32_bf16 v[62:65], v[130:133], v[178:181], v[62:65]
	v_mfma_f32_16x16x32_bf16 v[58:61], v[138:141], v[178:181], v[58:61]
	v_mfma_f32_16x16x32_bf16 v[46:49], v[130:133], v[186:189], v[46:49]
	v_mfma_f32_16x16x32_bf16 v[42:45], v[138:141], v[186:189], v[42:45]
	v_mfma_f32_16x16x32_bf16 v[30:33], v[130:133], v[230:233], v[30:33]
	v_mfma_f32_16x16x32_bf16 v[26:29], v[138:141], v[230:233], v[26:29]
	v_mfma_f32_16x16x32_bf16 v[14:17], v[130:133], v[238:241], v[14:17]
	v_mfma_f32_16x16x32_bf16 v[10:13], v[138:141], v[238:241], v[10:13]
	v_mfma_f32_16x16x32_bf16 v[62:65], v[134:137], v[182:185], v[62:65]
	v_mfma_f32_16x16x32_bf16 v[58:61], v[142:145], v[182:185], v[58:61]
	v_mfma_f32_16x16x32_bf16 v[46:49], v[134:137], v[190:193], v[46:49]
	v_mfma_f32_16x16x32_bf16 v[42:45], v[142:145], v[190:193], v[42:45]
	v_mfma_f32_16x16x32_bf16 v[30:33], v[134:137], v[234:237], v[30:33]
	v_mfma_f32_16x16x32_bf16 v[26:29], v[142:145], v[234:237], v[26:29]
	v_mfma_f32_16x16x32_bf16 v[14:17], v[134:137], v[242:245], v[14:17]
	v_mfma_f32_16x16x32_bf16 v[10:13], v[142:145], v[242:245], v[10:13]
	v_mfma_f32_16x16x32_bf16 v[54:57], v[162:165], v[178:181], v[54:57]
	v_mfma_f32_16x16x32_bf16 v[50:53], v[170:173], v[178:181], v[50:53]
	v_mfma_f32_16x16x32_bf16 v[38:41], v[162:165], v[186:189], v[38:41]
	v_mfma_f32_16x16x32_bf16 v[34:37], v[170:173], v[186:189], v[34:37]
	v_mfma_f32_16x16x32_bf16 v[22:25], v[162:165], v[230:233], v[22:25]
	v_mfma_f32_16x16x32_bf16 v[18:21], v[170:173], v[230:233], v[18:21]
	v_mfma_f32_16x16x32_bf16 v[6:9], v[162:165], v[238:241], v[6:9]
	v_mfma_f32_16x16x32_bf16 v[2:5], v[170:173], v[238:241], v[2:5]
	v_mfma_f32_16x16x32_bf16 v[54:57], v[166:169], v[182:185], v[54:57]
	v_mfma_f32_16x16x32_bf16 v[50:53], v[174:177], v[182:185], v[50:53]
	v_mfma_f32_16x16x32_bf16 v[38:41], v[166:169], v[190:193], v[38:41]
	v_mfma_f32_16x16x32_bf16 v[34:37], v[174:177], v[190:193], v[34:37]
	v_mfma_f32_16x16x32_bf16 v[22:25], v[166:169], v[234:237], v[22:25]
	v_mfma_f32_16x16x32_bf16 v[18:21], v[174:177], v[234:237], v[18:21]
	v_mfma_f32_16x16x32_bf16 v[6:9], v[166:169], v[242:245], v[6:9]
	v_mfma_f32_16x16x32_bf16 v[2:5], v[174:177], v[242:245], v[2:5]
	s_setprio 0
	s_barrier
	s_add_u32 s14, s14, 0x100
	s_addc_u32 s15, s15, 0
	s_add_u32 s20, s20, 0x100
	s_addc_u32 s21, s21, 0
	s_cmp_ge_u32 s26, s94
	s_mov_b32 s18, s26
	s_cbranch_scc0 .LBB0_282
	s_and_b64 vcc, exec, s[78:79]
	s_cbranch_vccz .LBB0_285
	s_barrier

; #define PG8_BAR __builtin_amdgcn_s_barrier()
; template <class Epi, class Sched, bool ALIGN_EPI = false, bool SP2 = false>
; __device__ __forceinline__ void gemm_phase(PG8_LAS unsigned char* lds, int tid_in, const Gemm g, const Sched& S, const Epi& E) {
;     ...
;         cur = nxt; cA = nA; cB = nB; ++ui;
;         if constexpr (ALIGN_EPI) { if (wr == 1) PG8_BAR; }
;     }
.LBB0_620:
	s_andn2_b64 vcc, exec, s[56:57]
	s_cbranch_vccnz .LBB0_269
	s_barrier
	s_branch .LBB0_269
	s_nop 0
	s_nop 0
	s_nop 0
	s_nop 0
	s_nop 0
	s_nop 0
	s_nop 0
	s_nop 0
	s_nop 0
	s_nop 0
	s_nop 0
	s_nop 0
	s_nop 0
	s_nop 0
	s_nop 0
	s_nop 0
	s_nop 0
	s_nop 0
	s_nop 0
	s_nop 0
	s_nop 0
	s_nop 0
	s_nop 0
	s_nop 0
	s_nop 0
	s_nop 0
	s_nop 0
	s_nop 0
	s_nop 0
	s_nop 0
	s_nop 0
	s_nop 0
	s_nop 0
	s_nop 0
	s_nop 0
	s_nop 0
	s_nop 0
	s_nop 0
	s_nop 0
	s_nop 0
	s_nop 0
	s_nop 0
	s_nop 0
	s_nop 0
	s_nop 0
	s_nop 0
	s_nop 0
	s_nop 0
	s_nop 0
	s_nop 0
	s_nop 0
	s_nop 0
	s_nop 0
	s_nop 0
	s_nop 0
	s_nop 0
	s_nop 0
	s_nop 0
	s_nop 0
	s_nop 0
	s_nop 0
	s_nop 0
	s_nop 0
	s_nop 0
	s_nop 0
	s_nop 0
	s_nop 0
	s_nop 0
	s_nop 0
	s_nop 0
	s_nop 0
	s_nop 0
	s_nop 0
	s_nop 0
	s_nop 0
	s_nop 0
	s_nop 0
	s_nop 0
	s_nop 0
	s_nop 0
	s_nop 0
	s_nop 0
	s_nop 0
	s_nop 0
	s_nop 0
	s_nop 0
	s_nop 0
	s_nop 0
	s_nop 0
	s_nop 0
	s_nop 0
	s_nop 0
	s_nop 0
	s_nop 0
	s_nop 0
	s_nop 0
	s_nop 0
	s_nop 0
	s_nop 0
	s_nop 0
	s_nop 0
	s_nop 0
	s_nop 0
	s_nop 0
	s_nop 0
	s_nop 0
	s_nop 0
	s_nop 0
	s_nop 0
	s_nop 0
	s_nop 0
	s_nop 0
	s_nop 0
	s_nop 0
	s_nop 0
	s_nop 0
	s_nop 0
	s_nop 0
	s_nop 0
	s_nop 0
	s_nop 0
	s_nop 0
	s_nop 0
	s_nop 0
	s_nop 0
	s_nop 0
	s_nop 0
	s_nop 0
	s_nop 0
	s_nop 0
	s_nop 0
	s_nop 0
	s_nop 0
	s_nop 0
	s_nop 0
	s_nop 0
	s_nop 0
	s_nop 0
	s_nop 0
	s_nop 0
	s_nop 0
	s_nop 0
	s_nop 0
	s_nop 0
	s_nop 0
	s_nop 0
	s_nop 0
	s_nop 0
	s_nop 0
	s_nop 0
	s_nop 0
	s_nop 0
	s_nop 0
	s_nop 0
	s_nop 0
	s_nop 0
	s_nop 0
	s_nop 0
	s_nop 0
	s_nop 0
	s_nop 0
	s_nop 0
	s_nop 0
	s_nop 0
	s_nop 0
	s_nop 0
	s_nop 0
	s_nop 0
	s_nop 0
	s_nop 0
	s_nop 0
	s_nop 0
	s_nop 0
	s_nop 0
	s_nop 0
	s_nop 0
	s_nop 0
	s_nop 0
	s_nop 0
	s_nop 0
	s_nop 0
	s_nop 0
	s_nop 0
	s_nop 0
	s_nop 0
	s_nop 0
	s_nop 0
	s_nop 0
	s_nop 0
	s_nop 0
	s_nop 0
	s_nop 0
	s_nop 0
	s_nop 0
	s_nop 0
	s_nop 0
	s_nop 0
	s_nop 0
	s_nop 0
	s_nop 0
	s_nop 0
	s_nop 0
	s_nop 0
	s_nop 0
	s_nop 0
	s_nop 0
	s_nop 0
	s_nop 0
	s_nop 0
	s_nop 0
	s_nop 0
	s_nop 0
	s_nop 0
	s_nop 0
	s_nop 0
	s_nop 0
	s_nop 0
	s_nop 0
	s_nop 0
	s_nop 0
	s_nop 0
	s_nop 0
	s_nop 0
	s_nop 0
	s_nop 0
	s_nop 0
	s_nop 0
	s_nop 0
	s_nop 0
	s_nop 0
	s_nop 0
	s_nop 0
	s_nop 0
	s_nop 0
	s_nop 0
	s_nop 0
	s_nop 0
	s_nop 0
	s_nop 0
	s_nop 0
	s_nop 0
	s_nop 0
	s_nop 0
	s_nop 0
	s_nop 0
	s_nop 0
	s_nop 0
	s_nop 0
	s_nop 0
	s_nop 0
	s_nop 0
	s_nop 0
	s_nop 0
	s_nop 0
	s_nop 0
	s_nop 0
	s_nop 0
	s_nop 0
	s_nop 0
	s_nop 0
	s_nop 0
	s_nop 0
	s_nop 0
	s_nop 0
	s_nop 0
	s_nop 0
	s_nop 0
	s_nop 0
	s_nop 0
	s_nop 0
	s_nop 0
	s_nop 0
	s_nop 0
	s_nop 0
	s_nop 0
	s_nop 0
	s_nop 0
	s_nop 0
	s_nop 0
	s_nop 0
	s_nop 0
	s_nop 0
	s_nop 0
	s_nop 0
	s_nop 0
	s_nop 0
	s_nop 0
	s_nop 0
	s_nop 0
	s_nop 0
	s_nop 0
	s_nop 0
	s_nop 0
	s_nop 0
	s_nop 0
	s_nop 0
	s_nop 0
	s_nop 0
	s_nop 0
	s_nop 0
	s_nop 0
	s_nop 0
	s_nop 0
	s_nop 0
	s_nop 0
	s_nop 0
	s_nop 0
	s_nop 0
	s_nop 0
	s_nop 0
	s_nop 0
	s_nop 0
	s_nop 0
	s_nop 0
	s_nop 0
	s_nop 0
	s_nop 0
	s_nop 0
	s_nop 0
	s_nop 0
	s_nop 0
	s_nop 0
	s_nop 0
	s_nop 0
	s_nop 0
	s_nop 0
	s_nop 0
	s_nop 0
	s_nop 0
	s_nop 0
	s_nop 0
	s_nop 0
	s_nop 0
	s_nop 0
	s_nop 0
	s_nop 0
	s_nop 0
	s_nop 0
	s_nop 0
	s_nop 0
	s_nop 0
	s_nop 0
	s_nop 0
	s_nop 0
	s_nop 0
	s_nop 0
	s_nop 0
	s_nop 0
	s_nop 0
	s_nop 0
	s_nop 0
	s_nop 0
	s_nop 0
	s_nop 0
	s_nop 0
	s_nop 0
	s_nop 0
	s_nop 0
	s_nop 0
	s_nop 0
	s_nop 0
	s_nop 0
	s_nop 0
	s_nop 0
	s_nop 0
	s_nop 0
	s_nop 0
	s_nop 0
	s_nop 0
	s_nop 0
	s_nop 0
	s_nop 0
	s_nop 0
	s_nop 0
	s_nop 0
	s_nop 0
	s_nop 0
	s_nop 0
	s_nop 0
	s_nop 0
	s_nop 0
	s_nop 0
	s_nop 0
	s_nop 0
	s_nop 0
	s_nop 0
	s_nop 0
	s_nop 0
	s_nop 0
	s_nop 0
	s_nop 0
	s_nop 0
	s_nop 0
	s_nop 0
	s_nop 0
	s_nop 0
	s_nop 0
	s_nop 0
	s_nop 0
	s_nop 0
	s_nop 0
	s_nop 0
	s_nop 0
	s_nop 0
	s_nop 0
	s_nop 0
	s_nop 0
	s_nop 0
	s_nop 0
	s_nop 0
	s_nop 0
	s_nop 0
	s_nop 0
	s_nop 0
	s_nop 0
	s_nop 0
	s_nop 0
	s_nop 0
	s_nop 0
	s_nop 0
	s_nop 0
	s_nop 0
	s_nop 0
	s_nop 0
	s_nop 0
	s_nop 0
	s_nop 0
	s_nop 0
	s_nop 0
	s_nop 0
	s_nop 0
	s_nop 0
	s_nop 0
	s_nop 0
	s_nop 0
	s_nop 0
	s_nop 0
	s_nop 0
	s_nop 0
	s_nop 0
	s_nop 0
	s_nop 0
	s_nop 0
	s_nop 0
	s_nop 0
	s_nop 0
	s_nop 0
	s_nop 0
	s_nop 0
	s_nop 0
	s_nop 0
	s_nop 0
	s_nop 0
	s_nop 0
	s_nop 0
	s_nop 0
	s_nop 0
	s_nop 0
	s_nop 0
	s_nop 0
	s_nop 0
	s_nop 0
	s_nop 0
	s_nop 0
	s_nop 0
	s_nop 0
	s_nop 0
	s_nop 0
	s_nop 0
	s_nop 0
	s_nop 0
	s_nop 0
	s_nop 0
	s_nop 0
	s_nop 0
	s_nop 0
	s_nop 0
	s_nop 0
	s_nop 0
	s_nop 0
	s_nop 0
	s_nop 0
	s_nop 0
	s_nop 0
	s_nop 0
	s_nop 0
	s_nop 0
	s_nop 0
	s_nop 0
	s_nop 0
	s_nop 0
	s_nop 0
	s_nop 0
	s_nop 0
	s_nop 0
	s_nop 0
	s_nop 0
	s_nop 0
	s_nop 0
	s_nop 0
	s_nop 0
	s_nop 0
	s_nop 0
	s_nop 0
	s_nop 0
	s_nop 0
	s_nop 0
	s_nop 0
	s_nop 0
	s_nop 0
	s_nop 0
	s_nop 0
	s_nop 0
	s_nop 0
	s_nop 0
	s_nop 0
	s_nop 0
	s_nop 0
	s_nop 0
	s_nop 0
	s_nop 0
	s_nop 0
	s_nop 0
	s_nop 0
	s_nop 0
	s_nop 0
	s_nop 0
	s_nop 0
	s_nop 0
	s_nop 0
	s_nop 0
	s_nop 0
	s_nop 0
	s_nop 0
	s_nop 0
	s_nop 0
	s_nop 0
	s_nop 0
	s_nop 0
	s_nop 0
	s_nop 0
	s_nop 0
	s_nop 0
	s_nop 0
	s_nop 0
	s_nop 0
	s_nop 0
	s_nop 0
	s_nop 0
	s_nop 0
	s_nop 0
	s_nop 0
	s_nop 0
	s_nop 0
	s_nop 0
	s_nop 0
	s_nop 0
	s_nop 0
	s_nop 0
	s_nop 0
	s_nop 0
	s_nop 0
	s_nop 0
	s_nop 0
	s_nop 0
	s_nop 0
	s_nop 0
	s_nop 0
	s_nop 0
	s_nop 0
	s_nop 0
	s_nop 0
	s_nop 0
	s_nop 0
	s_nop 0
	s_nop 0
	s_nop 0
	s_nop 0
	s_nop 0
	s_nop 0
	s_nop 0
	s_nop 0
	s_nop 0
	s_nop 0
	s_nop 0
	s_nop 0
	s_nop 0
	s_nop 0
	s_nop 0
	s_nop 0
	s_nop 0
	s_nop 0
	s_nop 0
	s_nop 0
	s_nop 0
	s_nop 0
	s_nop 0
	s_nop 0
	s_nop 0
	s_nop 0
	s_nop 0
	s_nop 0
	s_nop 0
	s_nop 0
	s_nop 0
	s_nop 0
	s_nop 0
	s_nop 0
	s_nop 0
	s_nop 0
	s_nop 0
	s_nop 0
	s_nop 0
	s_nop 0
	s_nop 0
; #define PG8_BAR __builtin_amdgcn_s_barrier()
; template <class Epi, class Sched, bool ALIGN_EPI = false, bool SP2 = false>
; __device__ __forceinline__ void gemm_phase(PG8_LAS unsigned char* lds, int tid_in, const Gemm g, const Sched& S, const Epi& E) {
;     ...
;         if constexpr (ALIGN_EPI) { if (wr == 1) PG8_BAR; }
;     }
	s_nop 0
	s_nop 0
	s_nop 0
	s_nop 0
	s_nop 0
	s_nop 0
	s_nop 0
	s_nop 0
	s_nop 0
	s_nop 0
	s_nop 0
	s_nop 0
	s_nop 0
	s_nop 0
	s_nop 0
	s_nop 0
	s_nop 0
	s_nop 0
	s_nop 0
	s_nop 0
	s_nop 0
	s_nop 0
	s_nop 0
	s_nop 0
	s_nop 0
	s_nop 0
	s_nop 0
	s_nop 0
	s_nop 0
	s_nop 0
	s_nop 0
	s_nop 0
	s_nop 0
	s_nop 0
	s_nop 0
	s_nop 0
	s_nop 0
	s_nop 0
	s_nop 0
	s_nop 0
	s_nop 0
	s_nop 0
	s_nop 0
	s_nop 0
	s_nop 0
	s_nop 0
	s_nop 0
	s_nop 0
	s_nop 0
	s_nop 0
	s_nop 0
	s_nop 0
	s_nop 0
	s_nop 0
	s_nop 0
	s_nop 0
	s_nop 0
	s_nop 0
	s_nop 0
	s_nop 0
	s_nop 0
	s_nop 0
	s_nop 0
	s_nop 0
	s_nop 0
	s_nop 0
	s_nop 0
	s_nop 0
	s_nop 0
	s_nop 0
	s_nop 0
	s_nop 0
	s_nop 0
	s_nop 0
	s_nop 0
	s_nop 0
	s_nop 0
	s_nop 0
	s_nop 0
	s_nop 0
	s_nop 0
	s_nop 0
	s_nop 0
	s_nop 0
	s_nop 0
	s_nop 0
	s_nop 0
	s_nop 0
	s_nop 0
	s_nop 0
	s_nop 0
	s_nop 0
	s_nop 0
	s_nop 0
	s_nop 0
	s_nop 0
	s_nop 0
	s_nop 0
	s_nop 0
	s_nop 0
	s_nop 0
	s_nop 0
	s_nop 0
	s_nop 0
	s_nop 0
	s_nop 0
	s_nop 0
	s_nop 0
	s_nop 0
	s_nop 0
	s_nop 0
	s_nop 0
	s_nop 0
	s_nop 0
	s_nop 0
	s_nop 0
	s_nop 0
	s_nop 0
	s_nop 0
	s_nop 0
	s_nop 0
	s_nop 0
	s_nop 0
	s_nop 0
	s_nop 0
	s_nop 0
	s_nop 0
	s_nop 0
	s_nop 0
	s_nop 0
	s_nop 0
	s_nop 0
	s_nop 0
	s_nop 0
	s_nop 0
	s_nop 0
	s_nop 0
	s_nop 0
	s_nop 0
	s_nop 0
	s_nop 0
	s_nop 0
	s_nop 0
	s_nop 0
	s_nop 0
	s_nop 0
	s_nop 0
	s_nop 0
	s_nop 0
	s_nop 0
	s_nop 0
	s_nop 0
	s_nop 0
	s_nop 0
	s_nop 0
	s_nop 0
	s_nop 0
	s_nop 0
	s_nop 0
	s_nop 0
	s_nop 0
	s_nop 0
	s_nop 0
	s_nop 0
	s_nop 0
	s_nop 0
	s_nop 0
	s_nop 0
	s_nop 0
	s_nop 0
	s_nop 0
	s_nop 0
	s_nop 0
	s_nop 0
	s_nop 0
	s_nop 0
	s_nop 0
	s_nop 0
	s_nop 0
	s_nop 0
	s_nop 0
	s_nop 0
	s_nop 0
	s_nop 0
	s_nop 0
	s_nop 0
	s_nop 0
	s_nop 0
	s_nop 0
	s_nop 0
	s_nop 0
	s_nop 0
	s_nop 0
	s_nop 0
	s_nop 0
	s_nop 0
	s_nop 0
	s_nop 0
	s_nop 0
	s_nop 0
	s_nop 0
	s_nop 0
	s_nop 0
	s_nop 0
	s_nop 0
	s_nop 0
	s_nop 0
	s_nop 0
	s_nop 0
	s_nop 0
	s_nop 0
	s_nop 0
	s_nop 0
	s_nop 0
	s_nop 0
	s_nop 0
	s_nop 0
	s_nop 0
	s_nop 0
	s_nop 0
	s_nop 0
	s_nop 0
	s_nop 0
	s_nop 0
	s_nop 0
	s_nop 0
	s_nop 0
	s_nop 0
	s_nop 0
	s_nop 0
	s_nop 0
	s_nop 0
	s_nop 0
	s_nop 0
	s_nop 0
	s_nop 0
	s_nop 0
	s_nop 0
	s_nop 0
	s_nop 0
	s_nop 0
	s_nop 0
	s_nop 0
	s_nop 0
	s_nop 0
	s_nop 0
	s_nop 0
	s_nop 0
	s_nop 0
	s_nop 0
	s_nop 0
	s_nop 0
	s_nop 0
	s_nop 0
	s_nop 0
	s_nop 0
	s_nop 0
	s_nop 0
	s_nop 0
	s_nop 0
	s_nop 0
	s_nop 0
	s_nop 0
	s_nop 0
	s_nop 0
	s_nop 0
	s_nop 0
	s_nop 0
	s_nop 0
	s_nop 0
	s_nop 0
	s_nop 0
	s_nop 0
	s_nop 0
	s_nop 0
	s_nop 0
	s_nop 0
	s_nop 0
	s_nop 0
	s_nop 0
	s_nop 0
	s_nop 0
	s_nop 0
	s_nop 0
	s_nop 0
	s_nop 0
	s_nop 0
	s_nop 0
	s_nop 0
	s_nop 0
	s_nop 0
	s_nop 0
	s_nop 0
	s_nop 0
	s_nop 0
	s_nop 0
	s_nop 0
	s_nop 0
	s_nop 0
	s_nop 0
	s_nop 0
	s_nop 0
	s_nop 0
	s_nop 0
	s_nop 0
	s_nop 0
	s_nop 0
	s_nop 0
	s_nop 0
	s_nop 0
	s_nop 0
	s_nop 0
	s_nop 0
	s_nop 0
	s_nop 0
	s_nop 0
	s_nop 0
	s_nop 0
	s_nop 0
	s_nop 0
	s_nop 0
	s_nop 0
	s_nop 0
	s_nop 0
	s_nop 0
	s_nop 0
	s_nop 0
	s_nop 0
	s_nop 0
	s_nop 0
	s_nop 0
	s_nop 0
	s_nop 0
	s_nop 0
	s_nop 0
	s_nop 0
	s_nop 0
	s_nop 0
	s_nop 0
	s_nop 0
	s_nop 0
	s_nop 0
	s_nop 0
	s_nop 0
	s_nop 0
	s_nop 0
	s_nop 0
	s_nop 0
	s_nop 0
	s_nop 0
	s_nop 0
	s_nop 0
	s_nop 0
	s_nop 0
	s_nop 0
	s_nop 0
	s_nop 0
	s_nop 0
	s_nop 0
	s_nop 0
	s_nop 0
	s_nop 0
	s_nop 0
	s_nop 0
	s_nop 0
	s_nop 0
	s_nop 0
	s_nop 0
	s_nop 0
	s_nop 0
	s_nop 0
	s_nop 0
	s_nop 0
	s_nop 0
	s_nop 0
	s_nop 0
	s_nop 0
	s_nop 0
	s_nop 0
	s_nop 0
	s_nop 0
	s_nop 0
	s_nop 0
	s_nop 0
	s_nop 0
	s_nop 0
	s_nop 0
	s_nop 0
	s_nop 0
	s_nop 0
	s_nop 0
	s_nop 0
	s_nop 0
	s_nop 0
	s_nop 0
	s_nop 0
	s_nop 0
	s_nop 0
	s_nop 0
	s_nop 0
	s_nop 0
	s_nop 0
	s_nop 0
	s_nop 0
	s_nop 0
	s_nop 0
	s_nop 0
	s_nop 0
	s_nop 0
	s_nop 0
	s_nop 0
	s_nop 0
	s_nop 0
	s_nop 0
	s_nop 0
	s_nop 0
	s_nop 0
	s_nop 0
	s_nop 0
	s_nop 0
	s_nop 0
	s_nop 0
	s_nop 0
	s_nop 0
	s_nop 0
	s_nop 0
	s_nop 0
	s_nop 0
	s_nop 0
	s_nop 0
	s_nop 0
	s_nop 0
	s_nop 0
	s_nop 0
	s_nop 0
	s_nop 0
	s_nop 0
	s_nop 0
	s_nop 0
	s_nop 0
	s_nop 0
	s_nop 0
	s_nop 0
	s_nop 0
	s_nop 0
	s_nop 0
	s_nop 0
	s_nop 0
	s_nop 0
	s_nop 0
	s_nop 0
	s_nop 0
	s_nop 0
	s_nop 0
	s_nop 0
	s_nop 0
	s_nop 0
	s_nop 0
	s_nop 0
	s_nop 0
	s_nop 0
	s_nop 0
	s_nop 0
	s_nop 0
	s_nop 0
	s_nop 0
	s_nop 0
	s_nop 0
	s_nop 0
	s_nop 0
	s_nop 0
	s_nop 0
	s_nop 0
	s_nop 0
	s_nop 0
	s_nop 0
	s_nop 0
	s_nop 0
	s_nop 0
	s_nop 0
	s_nop 0
	s_nop 0
	s_nop 0
	s_nop 0
	s_nop 0
	s_nop 0
	s_nop 0
	s_nop 0
	s_nop 0
	s_nop 0
	s_nop 0
	s_nop 0
	s_nop 0
	s_nop 0
	s_nop 0
	s_nop 0
	s_nop 0
	s_nop 0
	s_nop 0
	s_nop 0
	s_nop 0
	s_nop 0
	s_nop 0
	s_nop 0
	s_nop 0
	s_nop 0
	s_nop 0
	s_nop 0
	s_nop 0
	s_nop 0
	s_nop 0
	s_nop 0
	s_nop 0
	s_nop 0
	s_nop 0
	s_nop 0
	s_nop 0
	s_nop 0
	s_nop 0
	s_nop 0
	s_nop 0
	s_nop 0
	s_nop 0
	s_nop 0
	s_nop 0
	s_nop 0
	s_nop 0
	s_nop 0
	s_nop 0
	s_nop 0
	s_nop 0
	s_nop 0
	s_nop 0
	s_nop 0
	s_nop 0
	s_nop 0
	s_nop 0
	s_nop 0
	s_nop 0
	s_nop 0
	s_nop 0
	s_nop 0
	s_nop 0
	s_nop 0
	s_nop 0
	s_nop 0
	s_nop 0
	s_nop 0
	s_nop 0
	s_nop 0
	s_nop 0
	s_nop 0
	s_nop 0
	s_nop 0
	s_nop 0
	s_nop 0
	s_nop 0
	s_nop 0
	s_nop 0
	s_nop 0
	s_nop 0
	s_nop 0
	s_nop 0
	s_nop 0
	s_nop 0
	s_nop 0
	s_nop 0
	s_nop 0
	s_nop 0
	s_nop 0
	s_nop 0
	s_nop 0
	s_nop 0
	s_nop 0
	s_nop 0
	s_nop 0
	s_nop 0
	s_nop 0
	s_nop 0
	s_nop 0
	s_nop 0
	s_nop 0
	s_nop 0
	s_nop 0
	s_nop 0
	s_nop 0
	s_nop 0
	s_nop 0
	s_nop 0
	s_nop 0
	s_nop 0
	s_nop 0
	s_nop 0
	s_nop 0
	s_nop 0
	s_nop 0
	s_nop 0
	s_nop 0
	s_nop 0
	s_nop 0
	s_nop 0
	s_nop 0
	s_nop 0
	s_nop 0
	s_nop 0
	s_nop 0
	s_nop 0
	s_nop 0
	s_nop 0
	s_nop 0
	s_nop 0
	s_nop 0
	s_nop 0
	s_nop 0
	s_nop 0
	s_nop 0
	s_nop 0
	s_nop 0
	s_nop 0
	s_nop 0
	s_nop 0
	s_nop 0
	s_nop 0
	s_nop 0
	s_nop 0
	s_nop 0
	s_nop 0
; #define PG8_BAR __builtin_amdgcn_s_barrier()
; template <class Epi, class Sched, bool ALIGN_EPI = false, bool SP2 = false>
; __device__ __forceinline__ void gemm_phase(PG8_LAS unsigned char* lds, int tid_in, const Gemm g, const Sched& S, const Epi& E) {
;     ...
;         if constexpr (ALIGN_EPI) { if (wr == 1) PG8_BAR; }
;     }
	s_nop 0
	s_nop 0
	s_nop 0
	s_nop 0
	s_nop 0
	s_nop 0
	s_nop 0
	s_nop 0
	s_nop 0
	s_nop 0
	s_nop 0
	s_nop 0
	s_nop 0
	s_nop 0
	s_nop 0
	s_nop 0
	s_nop 0
	s_nop 0
	s_nop 0
	s_nop 0
	s_nop 0
	s_nop 0
	s_nop 0
	s_nop 0
	s_nop 0
	s_nop 0
	s_nop 0
	s_nop 0
	s_nop 0
	s_nop 0
	s_nop 0
	s_nop 0
	s_nop 0
	s_nop 0
	s_nop 0
	s_nop 0
	s_nop 0
	s_nop 0
	s_nop 0
	s_nop 0
	s_nop 0
	s_nop 0
	s_nop 0
	s_nop 0
	s_nop 0
	s_nop 0
	s_nop 0
	s_nop 0
	s_nop 0
	s_nop 0
	s_nop 0
	s_nop 0
	s_nop 0
	s_nop 0
	s_nop 0
	s_nop 0
	s_nop 0
	s_nop 0
	s_nop 0
	s_nop 0
	s_nop 0
	s_nop 0
	s_nop 0
	s_nop 0
	s_nop 0
	s_nop 0
	s_nop 0
	s_nop 0
	s_nop 0
	s_nop 0
	s_nop 0
	s_nop 0
	s_nop 0
	s_nop 0
	s_nop 0
	s_nop 0
	s_nop 0
	s_nop 0
	s_nop 0
	s_nop 0
	s_nop 0
	s_nop 0
	s_nop 0
	s_nop 0
	s_nop 0
	s_nop 0
	s_nop 0
	s_nop 0
	s_nop 0
	s_nop 0
	s_nop 0
	s_nop 0
	s_nop 0
	s_nop 0
	s_nop 0
	s_nop 0
	s_nop 0
	s_nop 0
	s_nop 0
	s_nop 0
	s_nop 0
	s_nop 0
	s_nop 0
	s_nop 0
	s_nop 0
	s_nop 0
	s_nop 0
	s_nop 0
	s_nop 0
	s_nop 0
	s_nop 0
	s_nop 0
	s_nop 0
	s_nop 0
	s_nop 0
	s_nop 0
	s_nop 0
	s_nop 0
	s_nop 0
	s_nop 0
	s_nop 0
	s_nop 0
	s_nop 0
	s_nop 0
	s_nop 0
	s_nop 0
	s_nop 0
	s_nop 0
	s_nop 0
	s_nop 0
	s_nop 0
	s_nop 0
	s_nop 0
	s_nop 0
	s_nop 0
	s_nop 0
	s_nop 0
	s_nop 0
	s_nop 0
	s_nop 0
	s_nop 0
	s_nop 0
	s_nop 0
	s_nop 0
	s_nop 0
	s_nop 0
	s_nop 0
	s_nop 0
	s_nop 0
	s_nop 0
	s_nop 0
	s_nop 0
	s_nop 0
	s_nop 0
	s_nop 0
	s_nop 0
	s_nop 0
	s_nop 0
	s_nop 0
	s_nop 0
	s_nop 0
	s_nop 0
	s_nop 0
	s_nop 0
	s_nop 0
	s_nop 0
	s_nop 0
	s_nop 0
	s_nop 0
	s_nop 0
	s_nop 0
	s_nop 0
	s_nop 0
	s_nop 0
	s_nop 0
	s_nop 0
	s_nop 0
	s_nop 0
	s_nop 0
	s_nop 0
	s_nop 0
	s_nop 0
	s_nop 0
	s_nop 0
	s_nop 0
	s_nop 0
	s_nop 0
	s_nop 0
	s_nop 0
	s_nop 0
	s_nop 0
	s_nop 0
	s_nop 0
	s_nop 0
	s_nop 0
	s_nop 0
	s_nop 0
	s_nop 0
	s_nop 0
	s_nop 0
	s_nop 0
	s_nop 0
	s_nop 0
	s_nop 0
	s_nop 0
	s_nop 0
	s_nop 0
	s_nop 0
	s_nop 0
	s_nop 0
	s_nop 0
	s_nop 0
	s_nop 0
	s_nop 0
	s_nop 0
	s_nop 0
	s_nop 0
	s_nop 0
	s_nop 0
	s_nop 0
	s_nop 0
	s_nop 0
	s_nop 0
	s_nop 0
	s_nop 0
	s_nop 0
	s_nop 0
	s_nop 0
	s_nop 0
	s_nop 0
	s_nop 0
	s_nop 0
	s_nop 0
	s_nop 0
	s_nop 0
	s_nop 0
	s_nop 0
	s_nop 0
	s_nop 0
	s_nop 0
	s_nop 0
	s_nop 0
	s_nop 0
	s_nop 0
	s_nop 0
	s_nop 0
	s_nop 0
	s_nop 0
	s_nop 0
	s_nop 0
	s_nop 0
	s_nop 0
	s_nop 0
	s_nop 0
	s_nop 0
	s_nop 0
	s_nop 0
	s_nop 0
	s_nop 0
	s_nop 0
	s_nop 0
	s_nop 0
	s_nop 0
	s_nop 0
	s_nop 0
	s_nop 0
	s_nop 0
	s_nop 0
	s_nop 0
	s_nop 0
	s_nop 0
	s_nop 0
	s_nop 0
	s_nop 0
	s_nop 0
	s_nop 0
	s_nop 0
	s_nop 0
	s_nop 0
	s_nop 0
	s_nop 0
	s_nop 0
	s_nop 0
	s_nop 0
	s_nop 0
	s_nop 0
	s_nop 0
	s_nop 0
	s_nop 0
	s_nop 0
	s_nop 0
	s_nop 0
	s_nop 0
	s_nop 0
	s_nop 0
	s_nop 0
	s_nop 0
	s_nop 0
	s_nop 0
	s_nop 0
	s_nop 0
	s_nop 0
	s_nop 0
	s_nop 0
	s_nop 0
	s_nop 0
	s_nop 0
	s_nop 0
	s_nop 0
	s_nop 0
	s_nop 0
	s_nop 0
	s_nop 0
	s_nop 0
	s_nop 0
	s_nop 0
	s_nop 0
	s_nop 0
	s_nop 0
	s_nop 0
	s_nop 0
	s_nop 0
	s_nop 0
	s_nop 0
	s_nop 0
	s_nop 0
	s_nop 0
	s_nop 0
	s_nop 0
	s_nop 0
	s_nop 0
	s_nop 0
	s_nop 0
	s_nop 0
	s_nop 0
	s_nop 0
	s_nop 0
	s_nop 0
	s_nop 0
	s_nop 0
	s_nop 0
	s_nop 0
	s_nop 0
	s_nop 0
	s_nop 0
	s_nop 0
	s_nop 0
	s_nop 0
	s_nop 0
	s_nop 0
	s_nop 0
	s_nop 0
	s_nop 0
	s_nop 0
	s_nop 0
	s_nop 0
	s_nop 0
	s_nop 0
	s_nop 0
	s_nop 0
	s_nop 0
	s_nop 0
	s_nop 0
	s_nop 0
	s_nop 0
	s_nop 0
	s_nop 0
	s_nop 0
	s_nop 0
	s_nop 0
	s_nop 0
	s_nop 0
	s_nop 0
	s_nop 0
	s_nop 0
	s_nop 0
	s_nop 0
	s_nop 0
	s_nop 0
	s_nop 0
	s_nop 0
	s_nop 0
	s_nop 0
	s_nop 0
	s_nop 0
	s_nop 0
	s_nop 0
	s_nop 0
	s_nop 0
	s_nop 0
	s_nop 0
	s_nop 0
	s_nop 0
	s_nop 0
	s_nop 0
	s_nop 0
	s_nop 0
	s_nop 0
	s_nop 0
	s_nop 0
	s_nop 0
	s_nop 0
	s_nop 0
	s_nop 0
	s_nop 0
	s_nop 0
	s_nop 0
	s_nop 0
	s_nop 0
; #define PG8_BAR __builtin_amdgcn_s_barrier()
; template <class Epi, class Sched, bool ALIGN_EPI = false, bool SP2 = false>
; __device__ __forceinline__ void gemm_phase(PG8_LAS unsigned char* lds, int tid_in, const Gemm g, const Sched& S, const Epi& E) {
;     ...
;         if constexpr (ALIGN_EPI) { if (wr == 1) PG8_BAR; }
;     }
	s_nop 0
	s_nop 0
	s_nop 0
	s_nop 0
	s_nop 0
	s_nop 0
	s_nop 0
	s_nop 0
	s_nop 0
	s_nop 0
	s_nop 0
	s_nop 0
	s_nop 0
	s_nop 0
	s_nop 0
	s_nop 0
	s_nop 0
	s_nop 0
	s_nop 0
	s_nop 0
	s_nop 0
	s_nop 0
	s_nop 0
	s_nop 0
	s_nop 0
	s_nop 0
	s_nop 0
	s_nop 0
	s_nop 0
	s_nop 0
	s_nop 0
	s_nop 0
	s_nop 0
	s_nop 0
	s_nop 0
	s_nop 0
	s_nop 0
	s_nop 0
	s_nop 0
	s_nop 0
	s_nop 0
	s_nop 0
	s_nop 0
	s_nop 0
	s_nop 0
	s_nop 0
	s_nop 0
	s_nop 0
	s_nop 0
	s_nop 0
	s_nop 0
	s_nop 0
	s_nop 0
	s_nop 0
	s_nop 0
	s_nop 0
	s_nop 0
	s_nop 0
	s_nop 0
	s_nop 0
	s_nop 0
	s_nop 0
	s_nop 0
	s_nop 0
	s_nop 0
	s_nop 0
	s_nop 0
	s_nop 0
	s_nop 0
	s_nop 0
	s_nop 0
	s_nop 0
	s_nop 0
	s_nop 0
	s_nop 0
	s_nop 0
	s_nop 0
	s_nop 0
	s_nop 0
	s_nop 0
	s_nop 0
	s_nop 0
	s_nop 0
	s_nop 0
	s_nop 0
	s_nop 0
	s_nop 0
	s_nop 0
	s_nop 0
	s_nop 0
	s_nop 0
	s_nop 0
	s_nop 0
	s_nop 0
	s_nop 0
	s_nop 0
	s_nop 0
	s_nop 0
	s_nop 0
	s_nop 0
	s_nop 0
	s_nop 0
	s_nop 0
	s_nop 0
	s_nop 0
	s_nop 0
	s_nop 0
	s_nop 0
	s_nop 0
	s_nop 0
	s_nop 0
	s_nop 0
	s_nop 0
	s_nop 0
	s_nop 0
	s_nop 0
	s_nop 0
	s_nop 0
	s_nop 0
	s_nop 0
	s_nop 0
	s_nop 0
	s_nop 0
	s_nop 0
	s_nop 0
	s_nop 0
	s_nop 0
	s_nop 0
	s_nop 0
	s_nop 0
	s_nop 0
	s_nop 0
	s_nop 0
	s_nop 0
	s_nop 0
	s_nop 0
	s_nop 0
	s_nop 0
	s_nop 0
	s_nop 0
	s_nop 0
	s_nop 0
	s_nop 0
	s_nop 0
	s_nop 0
	s_nop 0
	s_nop 0
	s_nop 0
	s_nop 0
	s_nop 0
	s_nop 0
	s_nop 0
	s_nop 0
	s_nop 0
	s_nop 0
	s_nop 0
	s_nop 0
	s_nop 0
	s_nop 0
	s_nop 0
	s_nop 0
	s_nop 0
	s_nop 0
	s_nop 0
	s_nop 0
	s_nop 0
	s_nop 0
	s_nop 0
	s_nop 0
	s_nop 0
	s_nop 0
	s_nop 0
	s_nop 0
	s_nop 0
	s_nop 0
	s_nop 0
	s_nop 0
	s_nop 0
	s_nop 0
	s_nop 0
	s_nop 0
	s_nop 0
	s_nop 0
	s_nop 0
	s_nop 0
	s_nop 0
	s_nop 0
	s_nop 0
	s_nop 0
	s_nop 0
	s_nop 0
	s_nop 0
	s_nop 0
	s_nop 0
	s_nop 0
	s_nop 0
	s_nop 0
	s_nop 0
	s_nop 0
	s_nop 0
	s_nop 0
	s_nop 0
	s_nop 0
	s_nop 0
	s_nop 0
	s_nop 0
	s_nop 0
	s_nop 0
	s_nop 0
	s_nop 0
	s_nop 0
	s_nop 0
	s_nop 0
	s_nop 0
	s_nop 0
	s_nop 0
	s_nop 0
	s_nop 0
	s_nop 0
	s_nop 0
	s_nop 0
	s_nop 0
	s_nop 0
	s_nop 0
	s_nop 0
	s_nop 0
	s_nop 0
	s_nop 0
	s_nop 0
	s_nop 0
	s_nop 0
	s_nop 0
	s_nop 0
	s_nop 0
	s_nop 0
	s_nop 0
	s_nop 0
	s_nop 0
	s_nop 0
	s_nop 0
	s_nop 0
	s_nop 0
	s_nop 0
	s_nop 0
	s_nop 0
	s_nop 0
	s_nop 0
	s_nop 0
	s_nop 0
	s_nop 0
	s_nop 0
	s_nop 0
	s_nop 0
	s_nop 0
	s_nop 0
	s_nop 0
	s_nop 0
	s_nop 0
	s_nop 0
	s_nop 0
	s_nop 0
	s_nop 0
	s_nop 0
	s_nop 0
	s_nop 0
	s_nop 0
	s_nop 0
	s_nop 0
	s_nop 0
	s_nop 0
	s_nop 0
	s_nop 0
	s_nop 0
	s_nop 0
	s_nop 0
	s_nop 0
	s_nop 0
	s_nop 0
	s_nop 0
	s_nop 0
	s_nop 0
	s_nop 0
	s_nop 0
	s_nop 0
	s_nop 0
	s_nop 0
	s_nop 0
	s_nop 0
	s_nop 0
	s_nop 0
	s_nop 0
	s_nop 0
	s_nop 0
	s_nop 0
	s_nop 0
	s_nop 0
	s_nop 0
	s_nop 0
	s_nop 0
	s_nop 0
	s_nop 0
	s_nop 0
	s_nop 0
	s_nop 0
	s_nop 0
	s_nop 0
	s_nop 0
	s_nop 0
	s_nop 0
	s_nop 0
	s_nop 0
	s_nop 0
	s_nop 0
	s_nop 0
	s_nop 0
	s_nop 0
	s_nop 0
	s_nop 0
	s_nop 0
	s_nop 0
	s_nop 0
	s_nop 0
	s_nop 0
	s_nop 0
	s_nop 0
	s_nop 0
	s_nop 0
	s_nop 0
	s_nop 0
	s_nop 0
	s_nop 0
	s_nop 0
	s_nop 0
	s_nop 0
	s_nop 0
	s_nop 0
	s_nop 0
	s_nop 0
	s_nop 0
	s_nop 0
	s_nop 0
	s_nop 0
	s_nop 0
	s_nop 0
	s_nop 0
	s_nop 0
	s_nop 0
	s_nop 0
	s_nop 0
	s_nop 0
	s_nop 0
	s_nop 0
	s_nop 0
	s_nop 0
	s_nop 0
	s_nop 0
	s_nop 0
	s_nop 0
	s_nop 0
	s_nop 0
	s_nop 0
	s_nop 0
	s_nop 0
	s_nop 0
	s_nop 0
	s_nop 0
	s_nop 0
	s_nop 0
	s_nop 0
	s_nop 0
	s_nop 0
	s_nop 0
	s_nop 0
	s_nop 0
	s_nop 0
	s_nop 0
	s_nop 0
	s_nop 0
	s_nop 0
	s_nop 0
	s_nop 0
	s_nop 0
	s_nop 0
	s_nop 0
	s_nop 0
	s_nop 0
	s_nop 0
	s_nop 0
	s_nop 0
	s_nop 0
	s_nop 0
	s_nop 0
	s_nop 0
	s_nop 0
	s_nop 0
	s_nop 0
	s_nop 0
	s_nop 0
	s_nop 0
	s_nop 0
	s_nop 0
	s_nop 0
	s_nop 0
	s_nop 0
	s_nop 0
	s_nop 0
	s_nop 0
	s_nop 0
	s_nop 0

; #define PG8_STAGE(bufoff, gbase, voff) do { _Pragma("unroll") for (int _i = 0; _i < 2; ++_i) \
;         __builtin_amdgcn_global_load_lds((const unsigned*)((const char*)(gbase) + (voff)[_i]), (PG8_LAS unsigned*)(lds + (bufoff) + ldsw + _i * 8192), 16, 0, 0); } while (0)
; #define PG8_LDA(dst, b, h) do { _Pragma("unroll") for (int m = 0; m < 4; ++m) _Pragma("unroll") for (int k = 0; k < 2; ++k) dst[m][k] = *(const PG8_LAS bf16x8*)(lds + PG8_SA(b, h) + aoff + m * 2048 + k * 1024); } while (0)
; #define PG8_LDB(dst, b, h) do { _Pragma("unroll") for (int n = 0; n < 2; ++n) _Pragma("unroll") for (int k = 0; k < 2; ++k) dst[n][k] = *(const PG8_LAS bf16x8*)(lds + PG8_SB(b, h) + boff + n * 2048 + k * 1024); } while (0)
; #define PG8_MMA(ai, bj, At, Bt) do { __builtin_amdgcn_s_setprio(1); _Pragma("unroll") for (int m = 0; m < 4; ++m) _Pragma("unroll") for (int n = 0; n < 2; ++n) _Pragma("unroll") for (int k = 0; k < 2; ++k) \
;         acc[ai][bj][m][n] = __builtin_amdgcn_mfma_f32_16x16x32_bf16(Bt[n][k], At[m][k], acc[ai][bj][m][n], 0, 0, 0); __builtin_amdgcn_s_setprio(0); } while (0)
; #define PG8_WAIT_V(n) asm volatile("s_waitcnt vmcnt(" #n ")" ::: "memory")
; #define PG8_WAIT_L(n) asm volatile("s_waitcnt lgkmcnt(" #n ")" ::: "memory")
; #define PG8_BAR __builtin_amdgcn_s_barrier()
; #define PG8_SCHED __builtin_amdgcn_sched_barrier(0)
; template <class Epi, class Sched, bool ALIGN_EPI = false, bool SP2 = false>
; __device__ __forceinline__ void gemm_phase(PG8_LAS unsigned char* lds, int tid_in, const Gemm g, const Sched& S, const Epi& E) {
;     ...
;             if constexpr (SP2) {
;             PG8_LDB(B0, 0, 0); PG8_LDB(B1, 0, 1); PG8_SCHED; PG8_LDA(At, 0, 0); PG8_STAGE(PG8_SA(1, 1), a1 + hstepA, voffA);
;             PG8_WAIT_V(8); PG8_WAIT_L(0); PG8_BAR; PG8_MMA(0, 0, At, B0); PG8_MMA(0, 1, At, B1); PG8_BAR; PG8_SCHED;
;             PG8_LDA(At, 0, 1); PG8_STAGE(PG8_SB(0, 0), b2, voffB); PG8_STAGE(PG8_SB(0, 1), b2 + hstepB, voffB); PG8_STAGE(PG8_SA(0, 0), a2, voffA);
;             PG8_WAIT_V(8); PG8_WAIT_L(0); PG8_BAR; PG8_MMA(1, 0, At, B0); PG8_MMA(1, 1, At, B1); PG8_BAR; PG8_SCHED;
.LBB0_670:
	s_add_i32 s48, s34, 2
	s_add_u32 s49, s30, 0x80
	s_addc_u32 s35, s31, 0
	s_add_i32 s55, 0, 0x10000
	s_cmp_eq_u32 s47, s34
	s_cselect_b32 s35, s25, s35
	s_cselect_b32 s34, s24, s49
	s_cselect_b32 s51, s29, s45
	s_cselect_b32 s50, s28, s44
	s_add_i32 s49, 0, 0x14000
	v_add_u32_e32 v142, s55, v230
	v_add_u32_e32 v158, s49, v230
	ds_read_b128 v[126:129], v142
	ds_read_b128 v[130:133], v142 offset:1024
	ds_read_b128 v[134:137], v142 offset:2048
	ds_read_b128 v[142:145], v142 offset:3072
	ds_read_b128 v[146:149], v158
	ds_read_b128 v[150:153], v158 offset:1024
	ds_read_b128 v[154:157], v158 offset:2048
	ds_read_b128 v[158:161], v158 offset:3072
	v_lshl_add_u64 v[194:195], s[30:31], 0, v[202:203]
	s_add_i32 m0, s7, 0xc000
	ds_read_b128 v[162:165], v232
	ds_read_b128 v[166:169], v232 offset:1024
	ds_read_b128 v[170:173], v232 offset:2048
	ds_read_b128 v[174:177], v232 offset:3072
	ds_read_b128 v[178:181], v232 offset:4096
	ds_read_b128 v[182:185], v232 offset:5120
	ds_read_b128 v[186:189], v232 offset:6144
	ds_read_b128 v[190:193], v232 offset:7168
	global_load_lds_dwordx4 v[194:195], off
	v_lshl_add_u64 v[194:195], s[30:31], 0, v[204:205]
	s_add_i32 m0, s7, 0xe000
	s_nop 0
	global_load_lds_dwordx4 v[194:195], off
	s_waitcnt vmcnt(8)
	s_waitcnt lgkmcnt(0)
	s_barrier
	s_setprio 1
	v_mfma_f32_16x16x32_bf16 v[138:141], v[126:129], v[162:165], v[138:141]
	v_mfma_f32_16x16x32_bf16 v[122:125], v[134:137], v[162:165], v[122:125]
	v_mfma_f32_16x16x32_bf16 v[114:117], v[126:129], v[170:173], v[114:117]
	v_mfma_f32_16x16x32_bf16 v[106:109], v[134:137], v[170:173], v[106:109]
	v_mfma_f32_16x16x32_bf16 v[98:101], v[126:129], v[178:181], v[98:101]
	v_mfma_f32_16x16x32_bf16 v[90:93], v[134:137], v[178:181], v[90:93]
	v_mfma_f32_16x16x32_bf16 v[82:85], v[126:129], v[186:189], v[82:85]
	v_mfma_f32_16x16x32_bf16 v[74:77], v[134:137], v[186:189], v[74:77]
	v_mfma_f32_16x16x32_bf16 v[138:141], v[130:133], v[166:169], v[138:141]
	v_mfma_f32_16x16x32_bf16 v[122:125], v[142:145], v[166:169], v[122:125]
	v_mfma_f32_16x16x32_bf16 v[114:117], v[130:133], v[174:177], v[114:117]
	v_mfma_f32_16x16x32_bf16 v[106:109], v[142:145], v[174:177], v[106:109]
	v_mfma_f32_16x16x32_bf16 v[98:101], v[130:133], v[182:185], v[98:101]
	v_mfma_f32_16x16x32_bf16 v[90:93], v[142:145], v[182:185], v[90:93]
	v_mfma_f32_16x16x32_bf16 v[82:85], v[130:133], v[190:193], v[82:85]
	v_mfma_f32_16x16x32_bf16 v[74:77], v[142:145], v[190:193], v[74:77]
	v_mfma_f32_16x16x32_bf16 v[118:121], v[146:149], v[162:165], v[118:121]
	v_mfma_f32_16x16x32_bf16 v[110:113], v[154:157], v[162:165], v[110:113]
	v_mfma_f32_16x16x32_bf16 v[102:105], v[146:149], v[170:173], v[102:105]
	v_mfma_f32_16x16x32_bf16 v[94:97], v[154:157], v[170:173], v[94:97]
	v_mfma_f32_16x16x32_bf16 v[86:89], v[146:149], v[178:181], v[86:89]
	v_mfma_f32_16x16x32_bf16 v[78:81], v[154:157], v[178:181], v[78:81]
	v_mfma_f32_16x16x32_bf16 v[70:73], v[146:149], v[186:189], v[70:73]
	v_mfma_f32_16x16x32_bf16 v[66:69], v[154:157], v[186:189], v[66:69]
	v_mfma_f32_16x16x32_bf16 v[118:121], v[150:153], v[166:169], v[118:121]
	v_mfma_f32_16x16x32_bf16 v[110:113], v[158:161], v[166:169], v[110:113]
	v_mfma_f32_16x16x32_bf16 v[102:105], v[150:153], v[174:177], v[102:105]
	v_mfma_f32_16x16x32_bf16 v[94:97], v[158:161], v[174:177], v[94:97]
	v_mfma_f32_16x16x32_bf16 v[86:89], v[150:153], v[182:185], v[86:89]
	v_mfma_f32_16x16x32_bf16 v[78:81], v[158:161], v[182:185], v[78:81]
	v_mfma_f32_16x16x32_bf16 v[70:73], v[150:153], v[190:193], v[70:73]
	v_mfma_f32_16x16x32_bf16 v[66:69], v[158:161], v[190:193], v[66:69]
	s_setprio 0
	s_barrier
	s_add_i32 s55, s55, s6
	v_lshl_add_u64 v[194:195], s[50:51], 0, v[0:1]
	s_mov_b32 m0, s55
	ds_read_b128 v[162:165], v232 offset:16384
	ds_read_b128 v[166:169], v232 offset:17408
	ds_read_b128 v[170:173], v232 offset:18432
	ds_read_b128 v[174:177], v232 offset:19456
	ds_read_b128 v[178:181], v232 offset:20480
	ds_read_b128 v[182:185], v232 offset:21504
	ds_read_b128 v[186:189], v232 offset:22528
	ds_read_b128 v[190:193], v232 offset:23552
	global_load_lds_dwordx4 v[194:195], off
	s_add_i32 m0, s55, 0x2000
	v_lshl_add_u64 v[196:197], s[50:51], 0, v[200:201]
	s_add_u32 s50, s50, s38
	s_addc_u32 s51, s51, 0
	s_add_i32 s49, s49, s6
	global_load_lds_dwordx4 v[196:197], off
	v_lshl_add_u64 v[198:199], s[50:51], 0, v[0:1]
	s_mov_b32 m0, s49
	v_lshl_add_u64 v[206:207], s[50:51], 0, v[200:201]
	global_load_lds_dwordx4 v[198:199], off
	s_add_i32 m0, s49, 0x2000
	v_lshl_add_u64 v[208:209], s[34:35], 0, v[0:1]
	global_load_lds_dwordx4 v[206:207], off
	s_mov_b32 m0, s7
	v_lshl_add_u64 v[210:211], s[34:35], 0, v[200:201]
	global_load_lds_dwordx4 v[208:209], off
	s_mov_b32 m0, s8
	s_nop 0
	global_load_lds_dwordx4 v[210:211], off
	s_waitcnt vmcnt(8)
	s_waitcnt lgkmcnt(0)
	s_barrier
; #define PG8_STAGE(bufoff, gbase, voff) do { _Pragma("unroll") for (int _i = 0; _i < 2; ++_i) \
;         __builtin_amdgcn_global_load_lds((const unsigned*)((const char*)(gbase) + (voff)[_i]), (PG8_LAS unsigned*)(lds + (bufoff) + ldsw + _i * 8192), 16, 0, 0); } while (0)
; #define PG8_LDA(dst, b, h) do { _Pragma("unroll") for (int m = 0; m < 4; ++m) _Pragma("unroll") for (int k = 0; k < 2; ++k) dst[m][k] = *(const PG8_LAS bf16x8*)(lds + PG8_SA(b, h) + aoff + m * 2048 + k * 1024); } while (0)
; #define PG8_LDB(dst, b, h) do { _Pragma("unroll") for (int n = 0; n < 2; ++n) _Pragma("unroll") for (int k = 0; k < 2; ++k) dst[n][k] = *(const PG8_LAS bf16x8*)(lds + PG8_SB(b, h) + boff + n * 2048 + k * 1024); } while (0)
; #define PG8_MMA(ai, bj, At, Bt) do { __builtin_amdgcn_s_setprio(1); _Pragma("unroll") for (int m = 0; m < 4; ++m) _Pragma("unroll") for (int n = 0; n < 2; ++n) _Pragma("unroll") for (int k = 0; k < 2; ++k) \
;         acc[ai][bj][m][n] = __builtin_amdgcn_mfma_f32_16x16x32_bf16(Bt[n][k], At[m][k], acc[ai][bj][m][n], 0, 0, 0); __builtin_amdgcn_s_setprio(0); } while (0)
; #define PG8_WAIT_V(n) asm volatile("s_waitcnt vmcnt(" #n ")" ::: "memory")
; #define PG8_WAIT_L(n) asm volatile("s_waitcnt lgkmcnt(" #n ")" ::: "memory")
; #define PG8_BAR __builtin_amdgcn_s_barrier()
; #define PG8_SCHED __builtin_amdgcn_sched_barrier(0)
; template <class Epi, class Sched, bool ALIGN_EPI = false, bool SP2 = false>
; __device__ __forceinline__ void gemm_phase(PG8_LAS unsigned char* lds, int tid_in, const Gemm g, const Sched& S, const Epi& E) {
;     ...
;             PG8_WAIT_V(8); PG8_WAIT_L(0); PG8_BAR; PG8_MMA(1, 0, At, B0); PG8_MMA(1, 1, At, B1); PG8_BAR; PG8_SCHED;
;             PG8_LDB(B0, 1, 0); PG8_LDB(B1, 1, 1); PG8_SCHED; PG8_LDA(At, 1, 0); PG8_STAGE(PG8_SA(0, 1), a2 + hstepA, voffA);
;             PG8_WAIT_V(8); PG8_WAIT_L(0); PG8_BAR; PG8_MMA(0, 0, At, B0); PG8_MMA(0, 1, At, B1); PG8_BAR; PG8_SCHED;
	s_setprio 1
	v_mfma_f32_16x16x32_bf16 v[62:65], v[126:129], v[162:165], v[62:65]
	v_mfma_f32_16x16x32_bf16 v[58:61], v[134:137], v[162:165], v[58:61]
	v_mfma_f32_16x16x32_bf16 v[50:53], v[126:129], v[170:173], v[50:53]
	v_mfma_f32_16x16x32_bf16 v[42:45], v[134:137], v[170:173], v[42:45]
	v_mfma_f32_16x16x32_bf16 v[34:37], v[126:129], v[178:181], v[34:37]
	v_mfma_f32_16x16x32_bf16 v[26:29], v[134:137], v[178:181], v[26:29]
	v_mfma_f32_16x16x32_bf16 v[18:21], v[126:129], v[186:189], v[18:21]
	v_mfma_f32_16x16x32_bf16 v[10:13], v[134:137], v[186:189], v[10:13]
	v_mfma_f32_16x16x32_bf16 v[62:65], v[130:133], v[166:169], v[62:65]
	v_mfma_f32_16x16x32_bf16 v[58:61], v[142:145], v[166:169], v[58:61]
	v_mfma_f32_16x16x32_bf16 v[50:53], v[130:133], v[174:177], v[50:53]
	v_mfma_f32_16x16x32_bf16 v[42:45], v[142:145], v[174:177], v[42:45]
	v_mfma_f32_16x16x32_bf16 v[34:37], v[130:133], v[182:185], v[34:37]
	v_mfma_f32_16x16x32_bf16 v[26:29], v[142:145], v[182:185], v[26:29]
	v_mfma_f32_16x16x32_bf16 v[18:21], v[130:133], v[190:193], v[18:21]
	v_mfma_f32_16x16x32_bf16 v[10:13], v[142:145], v[190:193], v[10:13]
	v_mfma_f32_16x16x32_bf16 v[54:57], v[146:149], v[162:165], v[54:57]
	v_mfma_f32_16x16x32_bf16 v[46:49], v[154:157], v[162:165], v[46:49]
	v_mfma_f32_16x16x32_bf16 v[38:41], v[146:149], v[170:173], v[38:41]
	v_mfma_f32_16x16x32_bf16 v[30:33], v[154:157], v[170:173], v[30:33]
	v_mfma_f32_16x16x32_bf16 v[22:25], v[146:149], v[178:181], v[22:25]
	v_mfma_f32_16x16x32_bf16 v[14:17], v[154:157], v[178:181], v[14:17]
	v_mfma_f32_16x16x32_bf16 v[6:9], v[146:149], v[186:189], v[6:9]
	v_mfma_f32_16x16x32_bf16 v[2:5], v[154:157], v[186:189], v[2:5]
	v_mfma_f32_16x16x32_bf16 v[54:57], v[150:153], v[166:169], v[54:57]
	v_mfma_f32_16x16x32_bf16 v[46:49], v[158:161], v[166:169], v[46:49]
	v_mfma_f32_16x16x32_bf16 v[38:41], v[150:153], v[174:177], v[38:41]
	v_mfma_f32_16x16x32_bf16 v[30:33], v[158:161], v[174:177], v[30:33]
	v_mfma_f32_16x16x32_bf16 v[22:25], v[150:153], v[182:185], v[22:25]
	v_mfma_f32_16x16x32_bf16 v[14:17], v[158:161], v[182:185], v[14:17]
	v_mfma_f32_16x16x32_bf16 v[6:9], v[150:153], v[190:193], v[6:9]
	v_mfma_f32_16x16x32_bf16 v[2:5], v[158:161], v[190:193], v[2:5]
	s_setprio 0
	s_barrier
	s_add_i32 s49, 0, 0x18000
	s_add_i32 s50, 0, 0x1c000
	v_add_u32_e32 v142, s49, v230
	v_add_u32_e32 v158, s50, v230
	ds_read_b128 v[126:129], v142
	ds_read_b128 v[130:133], v142 offset:1024
	ds_read_b128 v[134:137], v142 offset:2048
	ds_read_b128 v[142:145], v142 offset:3072
	ds_read_b128 v[146:149], v158
	ds_read_b128 v[150:153], v158 offset:1024
	ds_read_b128 v[154:157], v158 offset:2048
	ds_read_b128 v[158:161], v158 offset:3072
	s_add_u32 s34, s34, s38
	s_addc_u32 s35, s35, 0
	s_mov_b32 m0, s9
	v_lshl_add_u64 v[212:213], s[34:35], 0, v[0:1]
	ds_read_b128 v[162:165], v232 offset:32768
	ds_read_b128 v[166:169], v232 offset:33792
	ds_read_b128 v[170:173], v232 offset:34816
	ds_read_b128 v[174:177], v232 offset:35840
	ds_read_b128 v[178:181], v232 offset:36864
	ds_read_b128 v[182:185], v232 offset:37888
	ds_read_b128 v[186:189], v232 offset:38912
	ds_read_b128 v[190:193], v232 offset:39936
	global_load_lds_dwordx4 v[212:213], off
	v_lshl_add_u64 v[212:213], s[34:35], 0, v[200:201]
	s_mov_b32 m0, s26
	s_nop 0
	global_load_lds_dwordx4 v[212:213], off
	s_waitcnt vmcnt(8)
	s_waitcnt lgkmcnt(0)
	s_barrier
	s_setprio 1
	v_mfma_f32_16x16x32_bf16 v[138:141], v[126:129], v[162:165], v[138:141]
	v_mfma_f32_16x16x32_bf16 v[122:125], v[134:137], v[162:165], v[122:125]
	v_mfma_f32_16x16x32_bf16 v[114:117], v[126:129], v[170:173], v[114:117]
	v_mfma_f32_16x16x32_bf16 v[106:109], v[134:137], v[170:173], v[106:109]
	v_mfma_f32_16x16x32_bf16 v[98:101], v[126:129], v[178:181], v[98:101]
	v_mfma_f32_16x16x32_bf16 v[90:93], v[134:137], v[178:181], v[90:93]
	v_mfma_f32_16x16x32_bf16 v[82:85], v[126:129], v[186:189], v[82:85]
	v_mfma_f32_16x16x32_bf16 v[74:77], v[134:137], v[186:189], v[74:77]
	v_mfma_f32_16x16x32_bf16 v[138:141], v[130:133], v[166:169], v[138:141]
	v_mfma_f32_16x16x32_bf16 v[122:125], v[142:145], v[166:169], v[122:125]
	v_mfma_f32_16x16x32_bf16 v[114:117], v[130:133], v[174:177], v[114:117]
	v_mfma_f32_16x16x32_bf16 v[106:109], v[142:145], v[174:177], v[106:109]
	v_mfma_f32_16x16x32_bf16 v[98:101], v[130:133], v[182:185], v[98:101]
	v_mfma_f32_16x16x32_bf16 v[90:93], v[142:145], v[182:185], v[90:93]
	v_mfma_f32_16x16x32_bf16 v[82:85], v[130:133], v[190:193], v[82:85]
	v_mfma_f32_16x16x32_bf16 v[74:77], v[142:145], v[190:193], v[74:77]
	v_mfma_f32_16x16x32_bf16 v[118:121], v[146:149], v[162:165], v[118:121]
	v_mfma_f32_16x16x32_bf16 v[110:113], v[154:157], v[162:165], v[110:113]
	v_mfma_f32_16x16x32_bf16 v[102:105], v[146:149], v[170:173], v[102:105]
	v_mfma_f32_16x16x32_bf16 v[94:97], v[154:157], v[170:173], v[94:97]
	v_mfma_f32_16x16x32_bf16 v[86:89], v[146:149], v[178:181], v[86:89]
	v_mfma_f32_16x16x32_bf16 v[78:81], v[154:157], v[178:181], v[78:81]
	v_mfma_f32_16x16x32_bf16 v[70:73], v[146:149], v[186:189], v[70:73]
	v_mfma_f32_16x16x32_bf16 v[66:69], v[154:157], v[186:189], v[66:69]
	v_mfma_f32_16x16x32_bf16 v[118:121], v[150:153], v[166:169], v[118:121]
	v_mfma_f32_16x16x32_bf16 v[110:113], v[158:161], v[166:169], v[110:113]
	v_mfma_f32_16x16x32_bf16 v[102:105], v[150:153], v[174:177], v[102:105]
	v_mfma_f32_16x16x32_bf16 v[94:97], v[158:161], v[174:177], v[94:97]
	v_mfma_f32_16x16x32_bf16 v[86:89], v[150:153], v[182:185], v[86:89]
	v_mfma_f32_16x16x32_bf16 v[78:81], v[158:161], v[182:185], v[78:81]
	v_mfma_f32_16x16x32_bf16 v[70:73], v[150:153], v[190:193], v[70:73]
	v_mfma_f32_16x16x32_bf16 v[66:69], v[158:161], v[190:193], v[66:69]
	s_setprio 0
	s_barrier
; #define PG8_STAGE(bufoff, gbase, voff) do { _Pragma("unroll") for (int _i = 0; _i < 2; ++_i) \
;         __builtin_amdgcn_global_load_lds((const unsigned*)((const char*)(gbase) + (voff)[_i]), (PG8_LAS unsigned*)(lds + (bufoff) + ldsw + _i * 8192), 16, 0, 0); } while (0)
; #define PG8_LDA(dst, b, h) do { _Pragma("unroll") for (int m = 0; m < 4; ++m) _Pragma("unroll") for (int k = 0; k < 2; ++k) dst[m][k] = *(const PG8_LAS bf16x8*)(lds + PG8_SA(b, h) + aoff + m * 2048 + k * 1024); } while (0)
; #define PG8_MMA(ai, bj, At, Bt) do { __builtin_amdgcn_s_setprio(1); _Pragma("unroll") for (int m = 0; m < 4; ++m) _Pragma("unroll") for (int n = 0; n < 2; ++n) _Pragma("unroll") for (int k = 0; k < 2; ++k) \
;         acc[ai][bj][m][n] = __builtin_amdgcn_mfma_f32_16x16x32_bf16(Bt[n][k], At[m][k], acc[ai][bj][m][n], 0, 0, 0); __builtin_amdgcn_s_setprio(0); } while (0)
; #define PG8_WAIT_V(n) asm volatile("s_waitcnt vmcnt(" #n ")" ::: "memory")
; #define PG8_WAIT_L(n) asm volatile("s_waitcnt lgkmcnt(" #n ")" ::: "memory")
; #define PG8_BAR __builtin_amdgcn_s_barrier()
; #define PG8_SCHED __builtin_amdgcn_sched_barrier(0)
; template <class Epi, class Sched, bool ALIGN_EPI = false, bool SP2 = false>
; __device__ __forceinline__ void gemm_phase(PG8_LAS unsigned char* lds, int tid_in, const Gemm g, const Sched& S, const Epi& E) {
;     ...
;             PG8_LDA(At, 1, 1); PG8_STAGE(PG8_SB(1, 0), b3, voffB); PG8_STAGE(PG8_SB(1, 1), b3 + hstepB, voffB); PG8_STAGE(PG8_SA(1, 0), a3, voffA);
;             PG8_WAIT_V(8); PG8_WAIT_L(0); PG8_BAR; PG8_MMA(1, 0, At, B0); PG8_MMA(1, 1, At, B1); PG8_BAR; PG8_SCHED;
	s_add_i32 s34, s49, s6
	v_lshl_add_u64 v[194:195], v[194:195], 0, s[2:3]
	s_mov_b32 m0, s34
	ds_read_b128 v[162:165], v232 offset:49152
	ds_read_b128 v[166:169], v232 offset:50176
	ds_read_b128 v[170:173], v232 offset:51200
	ds_read_b128 v[174:177], v232 offset:52224
	ds_read_b128 v[178:181], v232 offset:53248
	ds_read_b128 v[182:185], v232 offset:54272
	ds_read_b128 v[186:189], v232 offset:55296
	ds_read_b128 v[190:193], v232 offset:56320
	global_load_lds_dwordx4 v[194:195], off
	v_lshl_add_u64 v[194:195], v[196:197], 0, s[2:3]
	s_add_i32 m0, s34, 0x2000
	s_add_i32 s34, s50, s6
	global_load_lds_dwordx4 v[194:195], off
	v_lshl_add_u64 v[194:195], v[198:199], 0, s[2:3]
	s_mov_b32 m0, s34
	s_nop 0
	global_load_lds_dwordx4 v[194:195], off
	v_lshl_add_u64 v[194:195], v[206:207], 0, s[2:3]
	s_add_i32 m0, s34, 0x2000
	s_nop 0
	global_load_lds_dwordx4 v[194:195], off
	v_lshl_add_u64 v[194:195], v[208:209], 0, s[2:3]
	s_mov_b32 m0, s33
	s_nop 0
	global_load_lds_dwordx4 v[194:195], off
	v_lshl_add_u64 v[194:195], v[210:211], 0, s[2:3]
	s_mov_b32 m0, s46
	s_nop 0
	global_load_lds_dwordx4 v[194:195], off
	s_waitcnt vmcnt(8)
	s_waitcnt lgkmcnt(0)
	s_barrier
	s_setprio 1
	v_mfma_f32_16x16x32_bf16 v[62:65], v[126:129], v[162:165], v[62:65]
	v_mfma_f32_16x16x32_bf16 v[58:61], v[134:137], v[162:165], v[58:61]
	v_mfma_f32_16x16x32_bf16 v[50:53], v[126:129], v[170:173], v[50:53]
	v_mfma_f32_16x16x32_bf16 v[42:45], v[134:137], v[170:173], v[42:45]
	v_mfma_f32_16x16x32_bf16 v[34:37], v[126:129], v[178:181], v[34:37]
	v_mfma_f32_16x16x32_bf16 v[26:29], v[134:137], v[178:181], v[26:29]
	v_mfma_f32_16x16x32_bf16 v[18:21], v[126:129], v[186:189], v[18:21]
	v_mfma_f32_16x16x32_bf16 v[10:13], v[134:137], v[186:189], v[10:13]
	v_mfma_f32_16x16x32_bf16 v[62:65], v[130:133], v[166:169], v[62:65]
	v_mfma_f32_16x16x32_bf16 v[58:61], v[142:145], v[166:169], v[58:61]
	v_mfma_f32_16x16x32_bf16 v[50:53], v[130:133], v[174:177], v[50:53]
	v_mfma_f32_16x16x32_bf16 v[42:45], v[142:145], v[174:177], v[42:45]
	v_mfma_f32_16x16x32_bf16 v[34:37], v[130:133], v[182:185], v[34:37]
	v_mfma_f32_16x16x32_bf16 v[26:29], v[142:145], v[182:185], v[26:29]
	v_mfma_f32_16x16x32_bf16 v[18:21], v[130:133], v[190:193], v[18:21]
	v_mfma_f32_16x16x32_bf16 v[10:13], v[142:145], v[190:193], v[10:13]
	v_mfma_f32_16x16x32_bf16 v[54:57], v[146:149], v[162:165], v[54:57]
	v_mfma_f32_16x16x32_bf16 v[46:49], v[154:157], v[162:165], v[46:49]
	v_mfma_f32_16x16x32_bf16 v[38:41], v[146:149], v[170:173], v[38:41]
	v_mfma_f32_16x16x32_bf16 v[30:33], v[154:157], v[170:173], v[30:33]
	v_mfma_f32_16x16x32_bf16 v[22:25], v[146:149], v[178:181], v[22:25]
	v_mfma_f32_16x16x32_bf16 v[14:17], v[154:157], v[178:181], v[14:17]
	v_mfma_f32_16x16x32_bf16 v[6:9], v[146:149], v[186:189], v[6:9]
	v_mfma_f32_16x16x32_bf16 v[2:5], v[154:157], v[186:189], v[2:5]
	v_mfma_f32_16x16x32_bf16 v[54:57], v[150:153], v[166:169], v[54:57]
	v_mfma_f32_16x16x32_bf16 v[46:49], v[158:161], v[166:169], v[46:49]
	v_mfma_f32_16x16x32_bf16 v[38:41], v[150:153], v[174:177], v[38:41]
	v_mfma_f32_16x16x32_bf16 v[30:33], v[158:161], v[174:177], v[30:33]
	v_mfma_f32_16x16x32_bf16 v[22:25], v[150:153], v[182:185], v[22:25]
	v_mfma_f32_16x16x32_bf16 v[14:17], v[158:161], v[182:185], v[14:17]
	v_mfma_f32_16x16x32_bf16 v[6:9], v[150:153], v[190:193], v[6:9]
	v_mfma_f32_16x16x32_bf16 v[2:5], v[158:161], v[190:193], v[2:5]
	s_setprio 0
	s_barrier
	s_add_u32 s30, s30, 0x100
	s_addc_u32 s31, s31, 0
	s_add_u32 s44, s44, 0x100
	s_addc_u32 s45, s45, 0
	s_cmp_ge_u32 s48, s27
	s_mov_b32 s34, s48
	s_cbranch_scc0 .LBB0_670
	s_and_b64 vcc, exec, s[22:23]
	s_cbranch_vccz .LBB0_673
	s_barrier

; __global__ void __launch_bounds__(512, 2) mk_fwd(Args a_) {
;     ...
;         if (ph + 1 < ph_hi) { if (ph >= 1000) grid.sync(); else xcd_barrier(xbar); }
;     }
.Lpost_getpc0:
	s_add_u32 s98, s98, (.LBB0_7-.Lpost_getpc0)&4294967295
	s_addc_u32 s99, s99, (.LBB0_7-.Lpost_getpc0)>>32
	s_setpc_b64 s[98:99]
	s_nop 0
	s_nop 0
	s_nop 0
	s_nop 0
	s_nop 0
	s_nop 0
	s_nop 0
	s_nop 0
	s_nop 0
	s_nop 0
	s_nop 0
	s_nop 0
	s_nop 0
	s_nop 0
	s_nop 0
	s_nop 0
	s_nop 0
	s_nop 0
	s_nop 0
	s_nop 0
	s_nop 0
	s_nop 0
	s_nop 0
	s_nop 0
	s_nop 0
	s_nop 0
	s_nop 0
	s_nop 0
	s_nop 0
	s_nop 0
	s_nop 0
	s_nop 0
	s_nop 0
	s_nop 0
	s_nop 0
	s_nop 0
	s_nop 0
	s_nop 0
	s_nop 0
	s_nop 0
	s_nop 0
	s_nop 0
	s_nop 0
	s_nop 0
	s_nop 0
	s_nop 0
	s_nop 0
	s_nop 0
	s_nop 0
	s_nop 0
	s_nop 0
	s_nop 0
	s_nop 0
	s_nop 0
	s_nop 0
	s_nop 0
	s_nop 0
	s_nop 0
	s_nop 0
	s_nop 0
	s_nop 0
	s_nop 0
	s_nop 0
	s_nop 0
	s_nop 0
	s_nop 0
	s_nop 0
	s_nop 0
	s_nop 0
	s_nop 0
	s_nop 0
	s_nop 0
	s_nop 0
	s_nop 0
	s_nop 0
	s_nop 0
	s_nop 0
	s_nop 0
	s_nop 0
	s_nop 0
	s_nop 0
	s_nop 0
	s_nop 0
	s_nop 0
	s_nop 0
	s_nop 0
	s_nop 0
	s_nop 0
	s_nop 0
	s_nop 0
	s_nop 0
	s_nop 0
	s_nop 0
	s_nop 0
	s_nop 0
	s_nop 0
	s_nop 0
	s_nop 0
	s_nop 0
	s_nop 0
	s_nop 0
	s_nop 0
	s_nop 0
	s_nop 0
	s_nop 0
	s_nop 0
	s_nop 0
	s_nop 0
	s_nop 0
	s_nop 0
	s_nop 0
	s_nop 0
	s_nop 0
	s_nop 0
	s_nop 0
	s_nop 0
	s_nop 0
	s_nop 0
	s_nop 0
	s_nop 0
	s_nop 0
	s_nop 0
	s_nop 0
	s_nop 0
	s_nop 0
	s_nop 0
	s_nop 0
	s_nop 0
	s_nop 0
	s_nop 0
	s_nop 0
	s_nop 0
	s_nop 0
	s_nop 0
	s_nop 0
	s_nop 0
	s_nop 0
	s_nop 0
	s_nop 0
	s_nop 0
	s_nop 0
	s_nop 0
	s_nop 0
	s_nop 0
	s_nop 0
	s_nop 0
	s_nop 0
	s_nop 0
	s_nop 0
	s_nop 0
	s_nop 0
	s_nop 0
	s_nop 0
	s_nop 0
	s_nop 0
	s_nop 0
	s_nop 0
	s_nop 0
	s_nop 0
	s_nop 0
	s_nop 0
	s_nop 0
	s_nop 0
	s_nop 0
	s_nop 0
	s_nop 0
	s_nop 0
	s_nop 0
	s_nop 0
	s_nop 0
	s_nop 0
	s_nop 0
	s_nop 0
	s_nop 0
	s_nop 0
	s_nop 0
	s_nop 0
	s_nop 0
	s_nop 0
	s_nop 0
	s_nop 0
	s_nop 0
	s_nop 0
	s_nop 0
	s_nop 0
	s_nop 0
	s_nop 0
	s_nop 0
	s_nop 0
	s_nop 0
	s_nop 0
	s_nop 0
	s_nop 0
	s_nop 0
	s_nop 0
	s_nop 0
	s_nop 0
	s_nop 0
	s_nop 0
	s_nop 0
	s_nop 0
	s_nop 0
	s_nop 0
	s_nop 0
	s_nop 0
	s_nop 0
	s_nop 0
	s_nop 0
	s_nop 0
	s_nop 0
	s_nop 0
	s_nop 0
	s_nop 0
	s_nop 0
	s_nop 0
	s_nop 0
	s_nop 0
	s_nop 0
	s_nop 0
	s_nop 0
	s_nop 0
	s_nop 0
	s_nop 0
	s_nop 0
	s_nop 0
	s_nop 0
	s_nop 0
	s_nop 0
	s_nop 0
	s_nop 0
	s_nop 0
	s_nop 0
	s_nop 0
	s_nop 0
	s_nop 0
	s_nop 0
	s_nop 0
	s_nop 0
	s_nop 0
	s_nop 0
	s_nop 0
	s_nop 0
	s_nop 0
	s_nop 0
	s_nop 0
	s_nop 0
	s_nop 0
	s_nop 0
	s_nop 0
	s_nop 0
	s_nop 0
	s_nop 0
	s_nop 0
	s_nop 0
	s_nop 0
	s_nop 0
	s_nop 0
	s_nop 0
	s_nop 0
	s_nop 0
	s_nop 0
	s_nop 0
	s_nop 0
	s_nop 0
	s_nop 0
	s_nop 0
	s_nop 0
	s_nop 0
	s_nop 0
	s_nop 0
	s_nop 0
	s_nop 0
	s_nop 0
	s_nop 0
	s_nop 0
	s_nop 0
	s_nop 0
	s_nop 0
	s_nop 0
	s_nop 0
	s_nop 0
	s_nop 0
	s_nop 0
	s_nop 0
	s_nop 0
	s_nop 0
	s_nop 0
	s_nop 0
	s_nop 0
	s_nop 0
	s_nop 0
	s_nop 0
	s_nop 0
	s_nop 0
	s_nop 0
	s_nop 0
	s_nop 0
	s_nop 0
	s_nop 0
	s_nop 0
	s_nop 0
	s_nop 0
	s_nop 0
	s_nop 0
	s_nop 0
	s_nop 0
	s_nop 0
	s_nop 0
	s_nop 0
	s_nop 0
	s_nop 0
	s_nop 0
	s_nop 0
	s_nop 0
	s_nop 0
	s_nop 0
	s_nop 0
	s_nop 0
	s_nop 0
	s_nop 0
	s_nop 0
	s_nop 0
	s_nop 0
	s_nop 0
	s_nop 0
	s_nop 0
	s_nop 0
	s_nop 0
	s_nop 0
	s_nop 0
	s_nop 0
	s_nop 0
	s_nop 0
	s_nop 0
	s_nop 0
	s_nop 0
	s_nop 0
	s_nop 0
	s_nop 0
	s_nop 0
	s_nop 0
	s_nop 0
	s_nop 0
	s_nop 0
	s_nop 0
	s_nop 0
	s_nop 0
	s_nop 0
	s_nop 0
	s_nop 0
	s_nop 0
	s_nop 0
	s_nop 0
	s_nop 0
	s_nop 0
	s_nop 0
	s_nop 0
	s_nop 0
	s_nop 0
	s_nop 0
	s_nop 0
	s_nop 0
	s_nop 0
	s_nop 0
	s_nop 0
	s_nop 0
	s_nop 0
	s_nop 0
	s_nop 0
	s_nop 0
	s_nop 0
	s_nop 0
	s_nop 0
	s_nop 0
	s_nop 0
	s_nop 0
	s_nop 0
	s_nop 0
	s_nop 0
	s_nop 0
	s_nop 0
	s_nop 0
	s_nop 0
	s_nop 0
	s_nop 0
	s_nop 0
	s_nop 0
	s_nop 0
	s_nop 0
	s_nop 0
	s_nop 0
	s_nop 0
	s_nop 0
	s_nop 0
	s_nop 0
	s_nop 0
	s_nop 0
	s_nop 0
	s_nop 0
	s_nop 0
	s_nop 0
	s_nop 0
	s_nop 0
	s_nop 0
	s_nop 0
	s_nop 0
	s_nop 0
	s_nop 0
	s_nop 0
	s_nop 0
	s_nop 0
	s_nop 0
	s_nop 0
	s_nop 0
	s_nop 0
	s_nop 0
	s_nop 0
	s_nop 0
	s_nop 0
	s_nop 0
	s_nop 0
	s_nop 0
	s_nop 0
	s_nop 0
	s_nop 0
	s_nop 0
	s_nop 0
	s_nop 0
	s_nop 0
	s_nop 0
	s_nop 0
	s_nop 0
	s_nop 0
	s_nop 0
	s_nop 0
	s_nop 0
	s_nop 0
	s_nop 0
	s_nop 0
	s_nop 0
	s_nop 0
	s_nop 0
	s_nop 0
	s_nop 0
	s_nop 0
	s_nop 0
	s_nop 0
	s_nop 0
	s_nop 0
	s_nop 0
	s_nop 0
	s_nop 0
	s_nop 0
	s_nop 0
	s_nop 0
	s_nop 0
	s_nop 0
	s_nop 0
	s_nop 0
	s_nop 0
	s_nop 0
	s_nop 0
	s_nop 0
	s_nop 0
	s_nop 0
	s_nop 0
	s_nop 0
	s_nop 0
	s_nop 0
	s_nop 0
	s_nop 0
	s_nop 0
	s_nop 0
	s_nop 0
	s_nop 0
	s_nop 0
	s_nop 0
	s_nop 0
	s_nop 0
	s_nop 0
	s_nop 0
	s_nop 0
	s_nop 0
	s_nop 0
	s_nop 0
	s_nop 0
	s_nop 0
	s_nop 0
	s_nop 0
	s_nop 0
	s_nop 0
	s_nop 0
	s_nop 0
	s_nop 0
	s_nop 0
	s_nop 0
	s_nop 0
	s_nop 0
	s_nop 0
	s_nop 0
	s_nop 0
	s_nop 0
	s_nop 0
	s_nop 0
	s_nop 0
	s_nop 0
	s_nop 0
	s_nop 0
	s_nop 0
	s_nop 0
	s_nop 0
